# scan recurrence: two state rows per lane (odd lanes hold the pair swapped), halves LDS record reads; x/y reductions halve at the first DPP stage
# speedup vs baseline: 1.0422x; 1.0422x over previous
; __device__ __forceinline__ void scan_half(const Params& p, LAS unsigned char* lds, int pi, int rh, int pass) {
;     ...
;         const int j = lane & 7, rowl = 8 * wave + (lane >> 3);
;         float* stp = (float*)(WSP + WS_ST) + ((size_t)(pi * 64 + 32 * rh + rowl)) * 64 + 8 * j;
;         f32x2 P01 = (f32x2){0.f, 0.f}, P23 = P01, P45 = P01, P67 = P01;
;         if (pass == 1) { const f32x4 a = *(const f32x4*)stp, c = *(const f32x4*)(stp + 4); P01 = a.xy; P23 = a.zw; P45 = c.xy; P67 = c.zw; }
;         const bool first = (lane & 7) == 0;
;         SCAN_BAR;
;         for (int it = 0; it < 66; ++it) {
;             if (it < 64) {
;                 const LAS float* rec = REC + (it & 1) * REC_BUF + 8 * j; const LAS float* vvp = VV + (it & 3) * 1024 + rowl; LAS float* yyp = YY + (it & 3) * 1024 + rowl;
;                 const LAS float* ssp = SSP + (it & 1) * 64 + 2 * (lane & 31);
;                 const float inv2 = __builtin_amdgcn_rcpf(fmaxf(ssp[0] + ssp[1], 1e-24f));
;                 f32x4 Rkk[2][2], Rw[2][2], Rka[2][2], Rkm[2][2], Rr[2][2]; float Rv[2];
;     ...
;                 LOADREC(0, 0);
;                 float yp = 0.f, yk0 = 0.f, yk1 = 0.f, yk2 = 0.f, yk3 = 0.f;
;     ...
; #pragma unroll
;                 for (int s = 0; s < 32; ++s) {
;                     const int c = s & 1, pc = c ^ 1;
;                     const float si = __int_as_float(__builtin_amdgcn_readlane(__float_as_int(inv2), s));
;                     f32x2 px, py, t01, t23, t45, t67; float x;
;                     f32x2 vv2; vv2.x = Rv[c]; asm volatile("" : "+v"(vv2));
;                     if (s >= 1) {
;                         VPKMUL(px, P01, Rkk[c][0].xy); VPKMUL(py, P01, Rr[pc][0].xy); VPKFMA(px, P23, Rkk[c][0].zw, px); VPKFMA(py, P23, Rr[pc][0].zw, py);
;                         VPKFMA(px, P45, Rkk[c][1].xy, px); VPKFMA(py, P45, Rr[pc][1].xy, py); VPKFMA(px, P67, Rkk[c][1].zw, px); VPKFMA(py, P67, Rr[pc][1].zw, py);
;                         VADD(x, px.x, px.y); VADD(yp, py.x, py.y);
;                     } else {
;                         VPKMUL(px, P01, Rkk[c][0].xy); VPKFMA(px, P23, Rkk[c][0].zw, px); VPKFMA(px, P45, Rkk[c][1].xy, px); VPKFMA(px, P67, Rkk[c][1].zw, px);
;                         VADD(x, px.x, px.y);
;                     }
;                     asm volatile("" ::: "memory");
;                     if (s + 1 < 32) LOADREC((s + 1) & 1, s + 1);
.LBB0_1048:
	s_waitcnt lgkmcnt(0)
	s_barrier
	v_and_b32_e32 v8, 15, v112
	v_lshrrev_b32_e32 v9, 4, v112
	v_lshlrev_b32_e32 v28, 4, v8
	v_lshlrev_b32_e32 v9, 3, v9
	v_lshl_add_u32 v9, s80, 5, v9
	v_and_b32_e32 v10, 1, v112
	v_lshl_add_u32 v11, v10, 2, v9
	v_xor_b32_e32 v10, 1, v10
	v_lshl_add_u32 v10, v10, 2, v9
	v_add_u32_e32 v29, s53, v11
	v_add_u32_e32 v26, s53, v10
	v_add_u32_e32 v30, s83, v11
	v_lshrrev_b32_e32 v8, 2, v8
	v_lshl_add_u32 v30, v8, 7, v30
	v_lshlrev_b32_e32 v10, 3, v113
	v_and_b32_e32 v10, 0xf8, v10
	v_add_u32_e32 v31, 0x21800, v10
	s_mov_b32 s9, 0
	s_waitcnt vmcnt(0)
.Lscan_it:
	s_cmp_gt_u32 s9, 63
	s_cbranch_scc1 .Lscan_bar
	s_and_b32 s10, s9, 1
	s_lshl_b32 s11, s10, 8
	v_add_u32_e32 v8, s11, v31
	ds_read_b64 v[8:9], v8
	s_mul_i32 s11, s10, 0xaa00
	s_and_b32 s10, s9, 3
	s_lshl_b32 s10, s10, 12
	v_add_u32_e32 v35, s11, v28
	v_add_u32_e32 v36, s10, v29
	v_add_u32_e32 v37, s10, v30
	v_add_u32_e32 v38, s10, v26
	ds_read_b128 v[48:51], v35 offset:0
	ds_read_b128 v[60:63], v35 offset:26112
	ds_read_b32 v92, v36 offset:0
	ds_read_b32 v93, v38 offset:0
	ds_read_b128 v[52:55], v35 offset:8704
	ds_read_b128 v[56:59], v35 offset:17408
	ds_read_b128 v[80:83], v35 offset:34816
	s_waitcnt lgkmcnt(7)
	v_add_f32_e32 v8, v8, v9
	v_max_f32_e32 v8, 0x179abe15, v8
	v_rcp_f32_e32 v34, v8
	s_waitcnt lgkmcnt(0)
	ds_read_b128 v[64:67], v35 offset:272
	ds_read_b128 v[76:79], v35 offset:26384
	ds_read_b32 v94, v36 offset:128
	ds_read_b32 v95, v38 offset:128
	ds_read_b128 v[68:71], v35 offset:8976
	ds_read_b128 v[72:75], v35 offset:17680
	ds_read_b128 v[84:87], v35 offset:35088
	v_pk_mul_f32 v[8:9], v[0:1], v[48:49] op_sel_hi:[1,0]
	v_pk_fma_f32 v[8:9], v[2:3], v[48:49], v[8:9] op_sel:[0,1,0] op_sel_hi:[1,1,1]
	v_pk_fma_f32 v[8:9], v[4:5], v[50:51], v[8:9] op_sel_hi:[1,0,1]
	v_pk_fma_f32 v[8:9], v[6:7], v[50:51], v[8:9] op_sel:[0,1,0] op_sel_hi:[1,1,1]
	v_readlane_b32 s10, v34, 0
	v_pk_mul_f32 v[16:17], v[92:93], v[60:61] op_sel_hi:[1,0]
	v_pk_mul_f32 v[18:19], v[92:93], v[60:61] op_sel:[0,1] op_sel_hi:[1,1]
	v_add_f32_dpp v8, v9, v8 quad_perm:[1,0,3,2] row_mask:0xf bank_mask:0xf bound_ctrl:1
	v_pk_mul_f32 v[20:21], v[92:93], v[62:63] op_sel_hi:[1,0]
	v_pk_mul_f32 v[22:23], v[92:93], v[62:63] op_sel:[0,1] op_sel_hi:[1,1]
	v_add_f32_dpp v8, v8, v8 quad_perm:[2,3,0,1] row_mask:0xf bank_mask:0xf bound_ctrl:1
	v_pk_fma_f32 v[0:1], v[0:1], v[52:53], v[16:17] op_sel_hi:[1,0,1]
	v_pk_fma_f32 v[2:3], v[2:3], v[52:53], v[18:19] op_sel:[0,1,0] op_sel_hi:[1,1,1]
	v_add_f32_dpp v8, v8, v8 row_ror:4 row_mask:0xf bank_mask:0xf bound_ctrl:1
	v_pk_fma_f32 v[4:5], v[4:5], v[54:55], v[20:21] op_sel_hi:[1,0,1]
	s_nop 0
	v_add_f32_dpp v8, v8, v8 row_ror:8 row_mask:0xf bank_mask:0xf bound_ctrl:1
	v_mul_f32_e32 v8, s10, v8
	v_pk_fma_f32 v[6:7], v[6:7], v[54:55], v[22:23] op_sel:[0,1,0] op_sel_hi:[1,1,1]
	s_nop 0
	v_mov_b32_dpp v9, v8 quad_perm:[1,0,3,2] row_mask:0xf bank_mask:0xf
	v_pk_fma_f32 v[0:1], v[8:9], v[56:57], v[0:1] op_sel_hi:[1,0,1] neg_lo:[1,0,0] neg_hi:[1,0,0]
	v_pk_fma_f32 v[2:3], v[8:9], v[56:57], v[2:3] op_sel:[0,1,0] op_sel_hi:[1,1,1] neg_lo:[1,0,0] neg_hi:[1,0,0]
	v_pk_fma_f32 v[4:5], v[8:9], v[58:59], v[4:5] op_sel_hi:[1,0,1] neg_lo:[1,0,0] neg_hi:[1,0,0]
	v_pk_fma_f32 v[6:7], v[8:9], v[58:59], v[6:7] op_sel:[0,1,0] op_sel_hi:[1,1,1] neg_lo:[1,0,0] neg_hi:[1,0,0]
	s_waitcnt lgkmcnt(0)
	ds_read_b128 v[48:51], v35 offset:544
	ds_read_b128 v[60:63], v35 offset:26656
	ds_read_b32 v92, v36 offset:256
	ds_read_b32 v93, v38 offset:256
	ds_read_b128 v[52:55], v35 offset:9248
	ds_read_b128 v[56:59], v35 offset:17952
	ds_read_b128 v[88:91], v35 offset:35360
	v_pk_mul_f32 v[8:9], v[0:1], v[64:65] op_sel_hi:[1,0]
	v_pk_mul_f32 v[10:11], v[0:1], v[80:81] op_sel_hi:[1,0]
	v_pk_fma_f32 v[8:9], v[2:3], v[64:65], v[8:9] op_sel:[0,1,0] op_sel_hi:[1,1,1]
	v_pk_fma_f32 v[10:11], v[2:3], v[80:81], v[10:11] op_sel:[0,1,0] op_sel_hi:[1,1,1]
	v_pk_fma_f32 v[8:9], v[4:5], v[66:67], v[8:9] op_sel_hi:[1,0,1]
	v_pk_fma_f32 v[10:11], v[4:5], v[82:83], v[10:11] op_sel_hi:[1,0,1]
	v_pk_fma_f32 v[8:9], v[6:7], v[66:67], v[8:9] op_sel:[0,1,0] op_sel_hi:[1,1,1]
	v_pk_fma_f32 v[10:11], v[6:7], v[82:83], v[10:11] op_sel:[0,1,0] op_sel_hi:[1,1,1]
	v_readlane_b32 s10, v34, 1
	v_pk_mul_f32 v[16:17], v[94:95], v[76:77] op_sel_hi:[1,0]
	v_pk_mul_f32 v[18:19], v[94:95], v[76:77] op_sel:[0,1] op_sel_hi:[1,1]
	v_add_f32_dpp v8, v9, v8 quad_perm:[1,0,3,2] row_mask:0xf bank_mask:0xf bound_ctrl:1
	v_add_f32_dpp v10, v11, v10 quad_perm:[1,0,3,2] row_mask:0xf bank_mask:0xf bound_ctrl:1
	v_pk_mul_f32 v[20:21], v[94:95], v[78:79] op_sel_hi:[1,0]
	v_pk_mul_f32 v[22:23], v[94:95], v[78:79] op_sel:[0,1] op_sel_hi:[1,1]
	v_add_f32_dpp v8, v8, v8 quad_perm:[2,3,0,1] row_mask:0xf bank_mask:0xf bound_ctrl:1
	v_add_f32_dpp v10, v10, v10 quad_perm:[2,3,0,1] row_mask:0xf bank_mask:0xf bound_ctrl:1
	v_pk_fma_f32 v[0:1], v[0:1], v[68:69], v[16:17] op_sel_hi:[1,0,1]
	v_pk_fma_f32 v[2:3], v[2:3], v[68:69], v[18:19] op_sel:[0,1,0] op_sel_hi:[1,1,1]
	v_add_f32_dpp v8, v8, v8 row_ror:4 row_mask:0xf bank_mask:0xf bound_ctrl:1
	v_add_f32_dpp v10, v10, v10 row_ror:4 row_mask:0xf bank_mask:0xf bound_ctrl:1
	v_pk_fma_f32 v[4:5], v[4:5], v[70:71], v[20:21] op_sel_hi:[1,0,1]
	v_add_f32_dpp v8, v8, v8 row_ror:8 row_mask:0xf bank_mask:0xf bound_ctrl:1
	v_mul_f32_e32 v8, s10, v8
	v_add_f32_dpp v96, v10, v10 row_ror:8 row_mask:0xf bank_mask:0x1 bound_ctrl:1
	v_pk_fma_f32 v[6:7], v[6:7], v[70:71], v[22:23] op_sel:[0,1,0] op_sel_hi:[1,1,1]
	v_mov_b32_dpp v9, v8 quad_perm:[1,0,3,2] row_mask:0xf bank_mask:0xf
	v_pk_fma_f32 v[0:1], v[8:9], v[72:73], v[0:1] op_sel_hi:[1,0,1] neg_lo:[1,0,0] neg_hi:[1,0,0]
	v_pk_fma_f32 v[2:3], v[8:9], v[72:73], v[2:3] op_sel:[0,1,0] op_sel_hi:[1,1,1] neg_lo:[1,0,0] neg_hi:[1,0,0]
	v_pk_fma_f32 v[4:5], v[8:9], v[74:75], v[4:5] op_sel_hi:[1,0,1] neg_lo:[1,0,0] neg_hi:[1,0,0]
	v_pk_fma_f32 v[6:7], v[8:9], v[74:75], v[6:7] op_sel:[0,1,0] op_sel_hi:[1,1,1] neg_lo:[1,0,0] neg_hi:[1,0,0]
	s_waitcnt lgkmcnt(0)
; __device__ __forceinline__ void scan_half(const Params& p, LAS unsigned char* lds, int pi, int rh, int pass) {
;     ...
;                 for (int s = 0; s < 32; ++s) {
;                     const int c = s & 1, pc = c ^ 1;
;                     const float si = __int_as_float(__builtin_amdgcn_readlane(__float_as_int(inv2), s));
;                     f32x2 px, py, t01, t23, t45, t67; float x;
;                     f32x2 vv2; vv2.x = Rv[c]; asm volatile("" : "+v"(vv2));
;                     if (s >= 1) {
;                         VPKMUL(px, P01, Rkk[c][0].xy); VPKMUL(py, P01, Rr[pc][0].xy); VPKFMA(px, P23, Rkk[c][0].zw, px); VPKFMA(py, P23, Rr[pc][0].zw, py);
;                         VPKFMA(px, P45, Rkk[c][1].xy, px); VPKFMA(py, P45, Rr[pc][1].xy, py); VPKFMA(px, P67, Rkk[c][1].zw, px); VPKFMA(py, P67, Rr[pc][1].zw, py);
;                         VADD(x, px.x, px.y); VADD(yp, py.x, py.y);
;                     } else {
;                         VPKMUL(px, P01, Rkk[c][0].xy); VPKFMA(px, P23, Rkk[c][0].zw, px); VPKFMA(px, P45, Rkk[c][1].xy, px); VPKFMA(px, P67, Rkk[c][1].zw, px);
;                         VADD(x, px.x, px.y);
;                     }
;                     asm volatile("" ::: "memory");
;                     if (s + 1 < 32) LOADREC((s + 1) & 1, s + 1);
;                     asm volatile("" ::: "memory");
;                     VPKMULBL(t01, vv2, Rkm[c][0].xy); VPKMULBL(t23, vv2, Rkm[c][0].zw);
;                     VDPP1(x); if (s >= 1) VDPP1(yp);
;                     VPKMULBL(t45, vv2, Rkm[c][1].xy); VPKMULBL(t67, vv2, Rkm[c][1].zw);
;                     VDPP2(x); if (s >= 1) VDPP2(yp);
;                     VPKFMA(P01, P01, Rw[c][0].xy, t01); VPKFMA(P23, P23, Rw[c][0].zw, t23);
;                     VDPP3(x); if (s >= 1) VDPP3(yp);
;                     VPKFMA(P45, P45, Rw[c][1].xy, t45); VPKFMA(P67, P67, Rw[c][1].zw, t67);
;                     if (s >= 1) { if (s - 1 < 8) YSHIFT(yk0); else if (s - 1 < 16) YSHIFT(yk1); else if (s - 1 < 24) YSHIFT(yk2); else YSHIFT(yk3); }
;                     x = x * si;
;                     f32x2 x2; x2.x = x; asm volatile("" : "+v"(x2));
;                     VPKNFMABL(P01, x2, Rka[c][0].xy, P01); VPKNFMABL(P23, x2, Rka[c][0].zw, P23); VPKNFMABL(P45, x2, Rka[c][1].xy, P45); VPKNFMABL(P67, x2, Rka[c][1].zw, P67);
;                 }
	ds_read_b128 v[64:67], v35 offset:816
	ds_read_b128 v[76:79], v35 offset:26928
	ds_read_b32 v94, v36 offset:384
	ds_read_b32 v95, v38 offset:384
	ds_read_b128 v[68:71], v35 offset:9520
	ds_read_b128 v[72:75], v35 offset:18224
	ds_read_b128 v[80:83], v35 offset:35632
	v_pk_mul_f32 v[8:9], v[0:1], v[48:49] op_sel_hi:[1,0]
	v_pk_mul_f32 v[10:11], v[0:1], v[84:85] op_sel_hi:[1,0]
	v_pk_fma_f32 v[8:9], v[2:3], v[48:49], v[8:9] op_sel:[0,1,0] op_sel_hi:[1,1,1]
	v_pk_fma_f32 v[10:11], v[2:3], v[84:85], v[10:11] op_sel:[0,1,0] op_sel_hi:[1,1,1]
	v_pk_fma_f32 v[8:9], v[4:5], v[50:51], v[8:9] op_sel_hi:[1,0,1]
	v_pk_fma_f32 v[10:11], v[4:5], v[86:87], v[10:11] op_sel_hi:[1,0,1]
	v_pk_fma_f32 v[8:9], v[6:7], v[50:51], v[8:9] op_sel:[0,1,0] op_sel_hi:[1,1,1]
	v_pk_fma_f32 v[10:11], v[6:7], v[86:87], v[10:11] op_sel:[0,1,0] op_sel_hi:[1,1,1]
	v_readlane_b32 s10, v34, 2
	v_pk_mul_f32 v[16:17], v[92:93], v[60:61] op_sel_hi:[1,0]
	v_pk_mul_f32 v[18:19], v[92:93], v[60:61] op_sel:[0,1] op_sel_hi:[1,1]
	v_add_f32_dpp v8, v9, v8 quad_perm:[1,0,3,2] row_mask:0xf bank_mask:0xf bound_ctrl:1
	v_add_f32_dpp v10, v11, v10 quad_perm:[1,0,3,2] row_mask:0xf bank_mask:0xf bound_ctrl:1
	v_pk_mul_f32 v[20:21], v[92:93], v[62:63] op_sel_hi:[1,0]
	v_pk_mul_f32 v[22:23], v[92:93], v[62:63] op_sel:[0,1] op_sel_hi:[1,1]
	v_add_f32_dpp v8, v8, v8 quad_perm:[2,3,0,1] row_mask:0xf bank_mask:0xf bound_ctrl:1
	v_add_f32_dpp v10, v10, v10 quad_perm:[2,3,0,1] row_mask:0xf bank_mask:0xf bound_ctrl:1
	v_pk_fma_f32 v[0:1], v[0:1], v[52:53], v[16:17] op_sel_hi:[1,0,1]
	v_pk_fma_f32 v[2:3], v[2:3], v[52:53], v[18:19] op_sel:[0,1,0] op_sel_hi:[1,1,1]
	v_add_f32_dpp v8, v8, v8 row_ror:4 row_mask:0xf bank_mask:0xf bound_ctrl:1
	v_add_f32_dpp v10, v10, v10 row_ror:4 row_mask:0xf bank_mask:0xf bound_ctrl:1
	v_pk_fma_f32 v[4:5], v[4:5], v[54:55], v[20:21] op_sel_hi:[1,0,1]
	v_add_f32_dpp v8, v8, v8 row_ror:8 row_mask:0xf bank_mask:0xf bound_ctrl:1
	v_mul_f32_e32 v8, s10, v8
	v_add_f32_dpp v96, v10, v10 row_ror:8 row_mask:0xf bank_mask:0x2 bound_ctrl:1
	v_pk_fma_f32 v[6:7], v[6:7], v[54:55], v[22:23] op_sel:[0,1,0] op_sel_hi:[1,1,1]
	v_mov_b32_dpp v9, v8 quad_perm:[1,0,3,2] row_mask:0xf bank_mask:0xf
	v_pk_fma_f32 v[0:1], v[8:9], v[56:57], v[0:1] op_sel_hi:[1,0,1] neg_lo:[1,0,0] neg_hi:[1,0,0]
	v_pk_fma_f32 v[2:3], v[8:9], v[56:57], v[2:3] op_sel:[0,1,0] op_sel_hi:[1,1,1] neg_lo:[1,0,0] neg_hi:[1,0,0]
	v_pk_fma_f32 v[4:5], v[8:9], v[58:59], v[4:5] op_sel_hi:[1,0,1] neg_lo:[1,0,0] neg_hi:[1,0,0]
	v_pk_fma_f32 v[6:7], v[8:9], v[58:59], v[6:7] op_sel:[0,1,0] op_sel_hi:[1,1,1] neg_lo:[1,0,0] neg_hi:[1,0,0]
	s_waitcnt lgkmcnt(0)
	ds_read_b128 v[48:51], v35 offset:1088
	ds_read_b128 v[60:63], v35 offset:27200
	ds_read_b32 v92, v36 offset:512
	ds_read_b32 v93, v38 offset:512
	ds_read_b128 v[52:55], v35 offset:9792
	ds_read_b128 v[56:59], v35 offset:18496
	ds_read_b128 v[84:87], v35 offset:35904
	v_pk_mul_f32 v[8:9], v[0:1], v[64:65] op_sel_hi:[1,0]
	v_pk_mul_f32 v[10:11], v[0:1], v[88:89] op_sel_hi:[1,0]
	v_pk_fma_f32 v[8:9], v[2:3], v[64:65], v[8:9] op_sel:[0,1,0] op_sel_hi:[1,1,1]
	v_pk_fma_f32 v[10:11], v[2:3], v[88:89], v[10:11] op_sel:[0,1,0] op_sel_hi:[1,1,1]
	v_pk_fma_f32 v[8:9], v[4:5], v[66:67], v[8:9] op_sel_hi:[1,0,1]
	v_pk_fma_f32 v[10:11], v[4:5], v[90:91], v[10:11] op_sel_hi:[1,0,1]
	v_pk_fma_f32 v[8:9], v[6:7], v[66:67], v[8:9] op_sel:[0,1,0] op_sel_hi:[1,1,1]
	v_pk_fma_f32 v[10:11], v[6:7], v[90:91], v[10:11] op_sel:[0,1,0] op_sel_hi:[1,1,1]
	v_readlane_b32 s10, v34, 3
	v_pk_mul_f32 v[16:17], v[94:95], v[76:77] op_sel_hi:[1,0]
	v_pk_mul_f32 v[18:19], v[94:95], v[76:77] op_sel:[0,1] op_sel_hi:[1,1]
	v_add_f32_dpp v8, v9, v8 quad_perm:[1,0,3,2] row_mask:0xf bank_mask:0xf bound_ctrl:1
	v_add_f32_dpp v10, v11, v10 quad_perm:[1,0,3,2] row_mask:0xf bank_mask:0xf bound_ctrl:1
	v_pk_mul_f32 v[20:21], v[94:95], v[78:79] op_sel_hi:[1,0]
	v_pk_mul_f32 v[22:23], v[94:95], v[78:79] op_sel:[0,1] op_sel_hi:[1,1]
	v_add_f32_dpp v8, v8, v8 quad_perm:[2,3,0,1] row_mask:0xf bank_mask:0xf bound_ctrl:1
	v_add_f32_dpp v10, v10, v10 quad_perm:[2,3,0,1] row_mask:0xf bank_mask:0xf bound_ctrl:1
	v_pk_fma_f32 v[0:1], v[0:1], v[68:69], v[16:17] op_sel_hi:[1,0,1]
	v_pk_fma_f32 v[2:3], v[2:3], v[68:69], v[18:19] op_sel:[0,1,0] op_sel_hi:[1,1,1]
	v_add_f32_dpp v8, v8, v8 row_ror:4 row_mask:0xf bank_mask:0xf bound_ctrl:1
	v_add_f32_dpp v10, v10, v10 row_ror:4 row_mask:0xf bank_mask:0xf bound_ctrl:1
	v_pk_fma_f32 v[4:5], v[4:5], v[70:71], v[20:21] op_sel_hi:[1,0,1]
	v_add_f32_dpp v8, v8, v8 row_ror:8 row_mask:0xf bank_mask:0xf bound_ctrl:1
	v_mul_f32_e32 v8, s10, v8
	v_add_f32_dpp v96, v10, v10 row_ror:8 row_mask:0xf bank_mask:0x4 bound_ctrl:1
	v_pk_fma_f32 v[6:7], v[6:7], v[70:71], v[22:23] op_sel:[0,1,0] op_sel_hi:[1,1,1]
	v_mov_b32_dpp v9, v8 quad_perm:[1,0,3,2] row_mask:0xf bank_mask:0xf
	v_pk_fma_f32 v[0:1], v[8:9], v[72:73], v[0:1] op_sel_hi:[1,0,1] neg_lo:[1,0,0] neg_hi:[1,0,0]
	v_pk_fma_f32 v[2:3], v[8:9], v[72:73], v[2:3] op_sel:[0,1,0] op_sel_hi:[1,1,1] neg_lo:[1,0,0] neg_hi:[1,0,0]
	v_pk_fma_f32 v[4:5], v[8:9], v[74:75], v[4:5] op_sel_hi:[1,0,1] neg_lo:[1,0,0] neg_hi:[1,0,0]
	v_pk_fma_f32 v[6:7], v[8:9], v[74:75], v[6:7] op_sel:[0,1,0] op_sel_hi:[1,1,1] neg_lo:[1,0,0] neg_hi:[1,0,0]
	s_waitcnt lgkmcnt(0)
; __device__ __forceinline__ void scan_half(const Params& p, LAS unsigned char* lds, int pi, int rh, int pass) {
;     ...
;                 for (int s = 0; s < 32; ++s) {
;                     const int c = s & 1, pc = c ^ 1;
;                     const float si = __int_as_float(__builtin_amdgcn_readlane(__float_as_int(inv2), s));
;                     f32x2 px, py, t01, t23, t45, t67; float x;
;                     f32x2 vv2; vv2.x = Rv[c]; asm volatile("" : "+v"(vv2));
;                     if (s >= 1) {
;                         VPKMUL(px, P01, Rkk[c][0].xy); VPKMUL(py, P01, Rr[pc][0].xy); VPKFMA(px, P23, Rkk[c][0].zw, px); VPKFMA(py, P23, Rr[pc][0].zw, py);
;                         VPKFMA(px, P45, Rkk[c][1].xy, px); VPKFMA(py, P45, Rr[pc][1].xy, py); VPKFMA(px, P67, Rkk[c][1].zw, px); VPKFMA(py, P67, Rr[pc][1].zw, py);
;                         VADD(x, px.x, px.y); VADD(yp, py.x, py.y);
;                     } else {
;                         VPKMUL(px, P01, Rkk[c][0].xy); VPKFMA(px, P23, Rkk[c][0].zw, px); VPKFMA(px, P45, Rkk[c][1].xy, px); VPKFMA(px, P67, Rkk[c][1].zw, px);
;                         VADD(x, px.x, px.y);
;                     }
;                     asm volatile("" ::: "memory");
;                     if (s + 1 < 32) LOADREC((s + 1) & 1, s + 1);
;                     asm volatile("" ::: "memory");
;                     VPKMULBL(t01, vv2, Rkm[c][0].xy); VPKMULBL(t23, vv2, Rkm[c][0].zw);
;                     VDPP1(x); if (s >= 1) VDPP1(yp);
;                     VPKMULBL(t45, vv2, Rkm[c][1].xy); VPKMULBL(t67, vv2, Rkm[c][1].zw);
;                     VDPP2(x); if (s >= 1) VDPP2(yp);
;                     VPKFMA(P01, P01, Rw[c][0].xy, t01); VPKFMA(P23, P23, Rw[c][0].zw, t23);
;                     VDPP3(x); if (s >= 1) VDPP3(yp);
;                     VPKFMA(P45, P45, Rw[c][1].xy, t45); VPKFMA(P67, P67, Rw[c][1].zw, t67);
;                     if (s >= 1) { if (s - 1 < 8) YSHIFT(yk0); else if (s - 1 < 16) YSHIFT(yk1); else if (s - 1 < 24) YSHIFT(yk2); else YSHIFT(yk3); }
;                     x = x * si;
;                     f32x2 x2; x2.x = x; asm volatile("" : "+v"(x2));
;                     VPKNFMABL(P01, x2, Rka[c][0].xy, P01); VPKNFMABL(P23, x2, Rka[c][0].zw, P23); VPKNFMABL(P45, x2, Rka[c][1].xy, P45); VPKNFMABL(P67, x2, Rka[c][1].zw, P67);
;                 }
	ds_read_b128 v[64:67], v35 offset:1360
	ds_read_b128 v[76:79], v35 offset:27472
	ds_read_b32 v94, v36 offset:640
	ds_read_b32 v95, v38 offset:640
	ds_read_b128 v[68:71], v35 offset:10064
	ds_read_b128 v[72:75], v35 offset:18768
	ds_read_b128 v[88:91], v35 offset:36176
	v_pk_mul_f32 v[8:9], v[0:1], v[48:49] op_sel_hi:[1,0]
	v_pk_mul_f32 v[10:11], v[0:1], v[80:81] op_sel_hi:[1,0]
	v_pk_fma_f32 v[8:9], v[2:3], v[48:49], v[8:9] op_sel:[0,1,0] op_sel_hi:[1,1,1]
	v_pk_fma_f32 v[10:11], v[2:3], v[80:81], v[10:11] op_sel:[0,1,0] op_sel_hi:[1,1,1]
	v_pk_fma_f32 v[8:9], v[4:5], v[50:51], v[8:9] op_sel_hi:[1,0,1]
	v_pk_fma_f32 v[10:11], v[4:5], v[82:83], v[10:11] op_sel_hi:[1,0,1]
	v_pk_fma_f32 v[8:9], v[6:7], v[50:51], v[8:9] op_sel:[0,1,0] op_sel_hi:[1,1,1]
	v_pk_fma_f32 v[10:11], v[6:7], v[82:83], v[10:11] op_sel:[0,1,0] op_sel_hi:[1,1,1]
	v_readlane_b32 s10, v34, 4
	v_pk_mul_f32 v[16:17], v[92:93], v[60:61] op_sel_hi:[1,0]
	v_pk_mul_f32 v[18:19], v[92:93], v[60:61] op_sel:[0,1] op_sel_hi:[1,1]
	v_add_f32_dpp v8, v9, v8 quad_perm:[1,0,3,2] row_mask:0xf bank_mask:0xf bound_ctrl:1
	v_add_f32_dpp v10, v11, v10 quad_perm:[1,0,3,2] row_mask:0xf bank_mask:0xf bound_ctrl:1
	v_pk_mul_f32 v[20:21], v[92:93], v[62:63] op_sel_hi:[1,0]
	v_pk_mul_f32 v[22:23], v[92:93], v[62:63] op_sel:[0,1] op_sel_hi:[1,1]
	v_add_f32_dpp v8, v8, v8 quad_perm:[2,3,0,1] row_mask:0xf bank_mask:0xf bound_ctrl:1
	v_add_f32_dpp v10, v10, v10 quad_perm:[2,3,0,1] row_mask:0xf bank_mask:0xf bound_ctrl:1
	v_pk_fma_f32 v[0:1], v[0:1], v[52:53], v[16:17] op_sel_hi:[1,0,1]
	v_pk_fma_f32 v[2:3], v[2:3], v[52:53], v[18:19] op_sel:[0,1,0] op_sel_hi:[1,1,1]
	v_add_f32_dpp v8, v8, v8 row_ror:4 row_mask:0xf bank_mask:0xf bound_ctrl:1
	v_add_f32_dpp v10, v10, v10 row_ror:4 row_mask:0xf bank_mask:0xf bound_ctrl:1
	v_pk_fma_f32 v[4:5], v[4:5], v[54:55], v[20:21] op_sel_hi:[1,0,1]
	v_add_f32_dpp v8, v8, v8 row_ror:8 row_mask:0xf bank_mask:0xf bound_ctrl:1
	v_mul_f32_e32 v8, s10, v8
	v_add_f32_dpp v96, v10, v10 row_ror:8 row_mask:0xf bank_mask:0x8 bound_ctrl:1
	v_pk_fma_f32 v[6:7], v[6:7], v[54:55], v[22:23] op_sel:[0,1,0] op_sel_hi:[1,1,1]
	v_mov_b32_dpp v9, v8 quad_perm:[1,0,3,2] row_mask:0xf bank_mask:0xf
	v_pk_fma_f32 v[0:1], v[8:9], v[56:57], v[0:1] op_sel_hi:[1,0,1] neg_lo:[1,0,0] neg_hi:[1,0,0]
	v_pk_fma_f32 v[2:3], v[8:9], v[56:57], v[2:3] op_sel:[0,1,0] op_sel_hi:[1,1,1] neg_lo:[1,0,0] neg_hi:[1,0,0]
	v_pk_fma_f32 v[4:5], v[8:9], v[58:59], v[4:5] op_sel_hi:[1,0,1] neg_lo:[1,0,0] neg_hi:[1,0,0]
	v_pk_fma_f32 v[6:7], v[8:9], v[58:59], v[6:7] op_sel:[0,1,0] op_sel_hi:[1,1,1] neg_lo:[1,0,0] neg_hi:[1,0,0]
	s_waitcnt lgkmcnt(0)
	ds_read_b128 v[48:51], v35 offset:1632
	ds_read_b128 v[60:63], v35 offset:27744
	ds_read_b32 v92, v36 offset:768
	ds_read_b32 v93, v38 offset:768
	ds_read_b128 v[52:55], v35 offset:10336
	ds_read_b128 v[56:59], v35 offset:19040
	ds_read_b128 v[80:83], v35 offset:36448
	v_pk_mul_f32 v[8:9], v[0:1], v[64:65] op_sel_hi:[1,0]
	v_pk_mul_f32 v[10:11], v[0:1], v[84:85] op_sel_hi:[1,0]
	v_pk_fma_f32 v[8:9], v[2:3], v[64:65], v[8:9] op_sel:[0,1,0] op_sel_hi:[1,1,1]
	v_pk_fma_f32 v[10:11], v[2:3], v[84:85], v[10:11] op_sel:[0,1,0] op_sel_hi:[1,1,1]
	v_pk_fma_f32 v[8:9], v[4:5], v[66:67], v[8:9] op_sel_hi:[1,0,1]
	v_pk_fma_f32 v[10:11], v[4:5], v[86:87], v[10:11] op_sel_hi:[1,0,1]
	v_pk_fma_f32 v[8:9], v[6:7], v[66:67], v[8:9] op_sel:[0,1,0] op_sel_hi:[1,1,1]
	v_pk_fma_f32 v[10:11], v[6:7], v[86:87], v[10:11] op_sel:[0,1,0] op_sel_hi:[1,1,1]
	v_readlane_b32 s10, v34, 5
	v_pk_mul_f32 v[16:17], v[94:95], v[76:77] op_sel_hi:[1,0]
	v_pk_mul_f32 v[18:19], v[94:95], v[76:77] op_sel:[0,1] op_sel_hi:[1,1]
	v_add_f32_dpp v8, v9, v8 quad_perm:[1,0,3,2] row_mask:0xf bank_mask:0xf bound_ctrl:1
	v_add_f32_dpp v10, v11, v10 quad_perm:[1,0,3,2] row_mask:0xf bank_mask:0xf bound_ctrl:1
	v_pk_mul_f32 v[20:21], v[94:95], v[78:79] op_sel_hi:[1,0]
	v_pk_mul_f32 v[22:23], v[94:95], v[78:79] op_sel:[0,1] op_sel_hi:[1,1]
	v_add_f32_dpp v8, v8, v8 quad_perm:[2,3,0,1] row_mask:0xf bank_mask:0xf bound_ctrl:1
	v_add_f32_dpp v10, v10, v10 quad_perm:[2,3,0,1] row_mask:0xf bank_mask:0xf bound_ctrl:1
	v_pk_fma_f32 v[0:1], v[0:1], v[68:69], v[16:17] op_sel_hi:[1,0,1]
	v_pk_fma_f32 v[2:3], v[2:3], v[68:69], v[18:19] op_sel:[0,1,0] op_sel_hi:[1,1,1]
	v_add_f32_dpp v8, v8, v8 row_ror:4 row_mask:0xf bank_mask:0xf bound_ctrl:1
	v_add_f32_dpp v10, v10, v10 row_ror:4 row_mask:0xf bank_mask:0xf bound_ctrl:1
	v_pk_fma_f32 v[4:5], v[4:5], v[70:71], v[20:21] op_sel_hi:[1,0,1]
	v_add_f32_dpp v8, v8, v8 row_ror:8 row_mask:0xf bank_mask:0xf bound_ctrl:1
	v_mul_f32_e32 v8, s10, v8
	v_add_f32_dpp v97, v10, v10 row_ror:8 row_mask:0xf bank_mask:0x1 bound_ctrl:1
	v_pk_fma_f32 v[6:7], v[6:7], v[70:71], v[22:23] op_sel:[0,1,0] op_sel_hi:[1,1,1]
	v_mov_b32_dpp v9, v8 quad_perm:[1,0,3,2] row_mask:0xf bank_mask:0xf
	v_pk_fma_f32 v[0:1], v[8:9], v[72:73], v[0:1] op_sel_hi:[1,0,1] neg_lo:[1,0,0] neg_hi:[1,0,0]
	v_pk_fma_f32 v[2:3], v[8:9], v[72:73], v[2:3] op_sel:[0,1,0] op_sel_hi:[1,1,1] neg_lo:[1,0,0] neg_hi:[1,0,0]
	v_pk_fma_f32 v[4:5], v[8:9], v[74:75], v[4:5] op_sel_hi:[1,0,1] neg_lo:[1,0,0] neg_hi:[1,0,0]
	v_pk_fma_f32 v[6:7], v[8:9], v[74:75], v[6:7] op_sel:[0,1,0] op_sel_hi:[1,1,1] neg_lo:[1,0,0] neg_hi:[1,0,0]
	s_waitcnt lgkmcnt(0)
; __device__ __forceinline__ void scan_half(const Params& p, LAS unsigned char* lds, int pi, int rh, int pass) {
;     ...
;                 for (int s = 0; s < 32; ++s) {
;                     const int c = s & 1, pc = c ^ 1;
;                     const float si = __int_as_float(__builtin_amdgcn_readlane(__float_as_int(inv2), s));
;                     f32x2 px, py, t01, t23, t45, t67; float x;
;                     f32x2 vv2; vv2.x = Rv[c]; asm volatile("" : "+v"(vv2));
;                     if (s >= 1) {
;                         VPKMUL(px, P01, Rkk[c][0].xy); VPKMUL(py, P01, Rr[pc][0].xy); VPKFMA(px, P23, Rkk[c][0].zw, px); VPKFMA(py, P23, Rr[pc][0].zw, py);
;                         VPKFMA(px, P45, Rkk[c][1].xy, px); VPKFMA(py, P45, Rr[pc][1].xy, py); VPKFMA(px, P67, Rkk[c][1].zw, px); VPKFMA(py, P67, Rr[pc][1].zw, py);
;                         VADD(x, px.x, px.y); VADD(yp, py.x, py.y);
;                     } else {
;                         VPKMUL(px, P01, Rkk[c][0].xy); VPKFMA(px, P23, Rkk[c][0].zw, px); VPKFMA(px, P45, Rkk[c][1].xy, px); VPKFMA(px, P67, Rkk[c][1].zw, px);
;                         VADD(x, px.x, px.y);
;                     }
;                     asm volatile("" ::: "memory");
;                     if (s + 1 < 32) LOADREC((s + 1) & 1, s + 1);
;                     asm volatile("" ::: "memory");
;                     VPKMULBL(t01, vv2, Rkm[c][0].xy); VPKMULBL(t23, vv2, Rkm[c][0].zw);
;                     VDPP1(x); if (s >= 1) VDPP1(yp);
;                     VPKMULBL(t45, vv2, Rkm[c][1].xy); VPKMULBL(t67, vv2, Rkm[c][1].zw);
;                     VDPP2(x); if (s >= 1) VDPP2(yp);
;                     VPKFMA(P01, P01, Rw[c][0].xy, t01); VPKFMA(P23, P23, Rw[c][0].zw, t23);
;                     VDPP3(x); if (s >= 1) VDPP3(yp);
;                     VPKFMA(P45, P45, Rw[c][1].xy, t45); VPKFMA(P67, P67, Rw[c][1].zw, t67);
;                     if (s >= 1) { if (s - 1 < 8) YSHIFT(yk0); else if (s - 1 < 16) YSHIFT(yk1); else if (s - 1 < 24) YSHIFT(yk2); else YSHIFT(yk3); }
;                     x = x * si;
;                     f32x2 x2; x2.x = x; asm volatile("" : "+v"(x2));
;                     VPKNFMABL(P01, x2, Rka[c][0].xy, P01); VPKNFMABL(P23, x2, Rka[c][0].zw, P23); VPKNFMABL(P45, x2, Rka[c][1].xy, P45); VPKNFMABL(P67, x2, Rka[c][1].zw, P67);
;                 }
	ds_read_b128 v[64:67], v35 offset:1904
	ds_read_b128 v[76:79], v35 offset:28016
	ds_read_b32 v94, v36 offset:896
	ds_read_b32 v95, v38 offset:896
	ds_read_b128 v[68:71], v35 offset:10608
	ds_read_b128 v[72:75], v35 offset:19312
	ds_read_b128 v[84:87], v35 offset:36720
	v_pk_mul_f32 v[8:9], v[0:1], v[48:49] op_sel_hi:[1,0]
	v_pk_mul_f32 v[10:11], v[0:1], v[88:89] op_sel_hi:[1,0]
	v_pk_fma_f32 v[8:9], v[2:3], v[48:49], v[8:9] op_sel:[0,1,0] op_sel_hi:[1,1,1]
	v_pk_fma_f32 v[10:11], v[2:3], v[88:89], v[10:11] op_sel:[0,1,0] op_sel_hi:[1,1,1]
	v_pk_fma_f32 v[8:9], v[4:5], v[50:51], v[8:9] op_sel_hi:[1,0,1]
	v_pk_fma_f32 v[10:11], v[4:5], v[90:91], v[10:11] op_sel_hi:[1,0,1]
	v_pk_fma_f32 v[8:9], v[6:7], v[50:51], v[8:9] op_sel:[0,1,0] op_sel_hi:[1,1,1]
	v_pk_fma_f32 v[10:11], v[6:7], v[90:91], v[10:11] op_sel:[0,1,0] op_sel_hi:[1,1,1]
	v_readlane_b32 s10, v34, 6
	v_pk_mul_f32 v[16:17], v[92:93], v[60:61] op_sel_hi:[1,0]
	v_pk_mul_f32 v[18:19], v[92:93], v[60:61] op_sel:[0,1] op_sel_hi:[1,1]
	v_add_f32_dpp v8, v9, v8 quad_perm:[1,0,3,2] row_mask:0xf bank_mask:0xf bound_ctrl:1
	v_add_f32_dpp v10, v11, v10 quad_perm:[1,0,3,2] row_mask:0xf bank_mask:0xf bound_ctrl:1
	v_pk_mul_f32 v[20:21], v[92:93], v[62:63] op_sel_hi:[1,0]
	v_pk_mul_f32 v[22:23], v[92:93], v[62:63] op_sel:[0,1] op_sel_hi:[1,1]
	v_add_f32_dpp v8, v8, v8 quad_perm:[2,3,0,1] row_mask:0xf bank_mask:0xf bound_ctrl:1
	v_add_f32_dpp v10, v10, v10 quad_perm:[2,3,0,1] row_mask:0xf bank_mask:0xf bound_ctrl:1
	v_pk_fma_f32 v[0:1], v[0:1], v[52:53], v[16:17] op_sel_hi:[1,0,1]
	v_pk_fma_f32 v[2:3], v[2:3], v[52:53], v[18:19] op_sel:[0,1,0] op_sel_hi:[1,1,1]
	v_add_f32_dpp v8, v8, v8 row_ror:4 row_mask:0xf bank_mask:0xf bound_ctrl:1
	v_add_f32_dpp v10, v10, v10 row_ror:4 row_mask:0xf bank_mask:0xf bound_ctrl:1
	v_pk_fma_f32 v[4:5], v[4:5], v[54:55], v[20:21] op_sel_hi:[1,0,1]
	v_add_f32_dpp v8, v8, v8 row_ror:8 row_mask:0xf bank_mask:0xf bound_ctrl:1
	v_mul_f32_e32 v8, s10, v8
	v_add_f32_dpp v97, v10, v10 row_ror:8 row_mask:0xf bank_mask:0x2 bound_ctrl:1
	v_pk_fma_f32 v[6:7], v[6:7], v[54:55], v[22:23] op_sel:[0,1,0] op_sel_hi:[1,1,1]
	v_mov_b32_dpp v9, v8 quad_perm:[1,0,3,2] row_mask:0xf bank_mask:0xf
	v_pk_fma_f32 v[0:1], v[8:9], v[56:57], v[0:1] op_sel_hi:[1,0,1] neg_lo:[1,0,0] neg_hi:[1,0,0]
	v_pk_fma_f32 v[2:3], v[8:9], v[56:57], v[2:3] op_sel:[0,1,0] op_sel_hi:[1,1,1] neg_lo:[1,0,0] neg_hi:[1,0,0]
	v_pk_fma_f32 v[4:5], v[8:9], v[58:59], v[4:5] op_sel_hi:[1,0,1] neg_lo:[1,0,0] neg_hi:[1,0,0]
	v_pk_fma_f32 v[6:7], v[8:9], v[58:59], v[6:7] op_sel:[0,1,0] op_sel_hi:[1,1,1] neg_lo:[1,0,0] neg_hi:[1,0,0]
	s_waitcnt lgkmcnt(0)
	ds_read_b128 v[48:51], v35 offset:2176
	ds_read_b128 v[60:63], v35 offset:28288
	ds_read_b32 v92, v36 offset:1024
	ds_read_b32 v93, v38 offset:1024
	ds_read_b128 v[52:55], v35 offset:10880
	ds_read_b128 v[56:59], v35 offset:19584
	ds_read_b128 v[88:91], v35 offset:36992
	v_pk_mul_f32 v[8:9], v[0:1], v[64:65] op_sel_hi:[1,0]
	v_pk_mul_f32 v[10:11], v[0:1], v[80:81] op_sel_hi:[1,0]
	v_pk_fma_f32 v[8:9], v[2:3], v[64:65], v[8:9] op_sel:[0,1,0] op_sel_hi:[1,1,1]
	v_pk_fma_f32 v[10:11], v[2:3], v[80:81], v[10:11] op_sel:[0,1,0] op_sel_hi:[1,1,1]
	v_pk_fma_f32 v[8:9], v[4:5], v[66:67], v[8:9] op_sel_hi:[1,0,1]
	v_pk_fma_f32 v[10:11], v[4:5], v[82:83], v[10:11] op_sel_hi:[1,0,1]
	v_pk_fma_f32 v[8:9], v[6:7], v[66:67], v[8:9] op_sel:[0,1,0] op_sel_hi:[1,1,1]
	v_pk_fma_f32 v[10:11], v[6:7], v[82:83], v[10:11] op_sel:[0,1,0] op_sel_hi:[1,1,1]
	v_readlane_b32 s10, v34, 7
	v_pk_mul_f32 v[16:17], v[94:95], v[76:77] op_sel_hi:[1,0]
	v_pk_mul_f32 v[18:19], v[94:95], v[76:77] op_sel:[0,1] op_sel_hi:[1,1]
	v_add_f32_dpp v8, v9, v8 quad_perm:[1,0,3,2] row_mask:0xf bank_mask:0xf bound_ctrl:1
	v_add_f32_dpp v10, v11, v10 quad_perm:[1,0,3,2] row_mask:0xf bank_mask:0xf bound_ctrl:1
	v_pk_mul_f32 v[20:21], v[94:95], v[78:79] op_sel_hi:[1,0]
	v_pk_mul_f32 v[22:23], v[94:95], v[78:79] op_sel:[0,1] op_sel_hi:[1,1]
	v_add_f32_dpp v8, v8, v8 quad_perm:[2,3,0,1] row_mask:0xf bank_mask:0xf bound_ctrl:1
	v_add_f32_dpp v10, v10, v10 quad_perm:[2,3,0,1] row_mask:0xf bank_mask:0xf bound_ctrl:1
	v_pk_fma_f32 v[0:1], v[0:1], v[68:69], v[16:17] op_sel_hi:[1,0,1]
	v_pk_fma_f32 v[2:3], v[2:3], v[68:69], v[18:19] op_sel:[0,1,0] op_sel_hi:[1,1,1]
	v_add_f32_dpp v8, v8, v8 row_ror:4 row_mask:0xf bank_mask:0xf bound_ctrl:1
	v_add_f32_dpp v10, v10, v10 row_ror:4 row_mask:0xf bank_mask:0xf bound_ctrl:1
	v_pk_fma_f32 v[4:5], v[4:5], v[70:71], v[20:21] op_sel_hi:[1,0,1]
	v_add_f32_dpp v8, v8, v8 row_ror:8 row_mask:0xf bank_mask:0xf bound_ctrl:1
	v_mul_f32_e32 v8, s10, v8
	v_add_f32_dpp v97, v10, v10 row_ror:8 row_mask:0xf bank_mask:0x4 bound_ctrl:1
	v_pk_fma_f32 v[6:7], v[6:7], v[70:71], v[22:23] op_sel:[0,1,0] op_sel_hi:[1,1,1]
	v_mov_b32_dpp v9, v8 quad_perm:[1,0,3,2] row_mask:0xf bank_mask:0xf
	v_pk_fma_f32 v[0:1], v[8:9], v[72:73], v[0:1] op_sel_hi:[1,0,1] neg_lo:[1,0,0] neg_hi:[1,0,0]
	v_pk_fma_f32 v[2:3], v[8:9], v[72:73], v[2:3] op_sel:[0,1,0] op_sel_hi:[1,1,1] neg_lo:[1,0,0] neg_hi:[1,0,0]
	v_pk_fma_f32 v[4:5], v[8:9], v[74:75], v[4:5] op_sel_hi:[1,0,1] neg_lo:[1,0,0] neg_hi:[1,0,0]
	v_pk_fma_f32 v[6:7], v[8:9], v[74:75], v[6:7] op_sel:[0,1,0] op_sel_hi:[1,1,1] neg_lo:[1,0,0] neg_hi:[1,0,0]
	s_waitcnt lgkmcnt(0)
; __device__ __forceinline__ void scan_half(const Params& p, LAS unsigned char* lds, int pi, int rh, int pass) {
;     ...
;                 for (int s = 0; s < 32; ++s) {
;                     const int c = s & 1, pc = c ^ 1;
;                     const float si = __int_as_float(__builtin_amdgcn_readlane(__float_as_int(inv2), s));
;                     f32x2 px, py, t01, t23, t45, t67; float x;
;                     f32x2 vv2; vv2.x = Rv[c]; asm volatile("" : "+v"(vv2));
;                     if (s >= 1) {
;                         VPKMUL(px, P01, Rkk[c][0].xy); VPKMUL(py, P01, Rr[pc][0].xy); VPKFMA(px, P23, Rkk[c][0].zw, px); VPKFMA(py, P23, Rr[pc][0].zw, py);
;                         VPKFMA(px, P45, Rkk[c][1].xy, px); VPKFMA(py, P45, Rr[pc][1].xy, py); VPKFMA(px, P67, Rkk[c][1].zw, px); VPKFMA(py, P67, Rr[pc][1].zw, py);
;                         VADD(x, px.x, px.y); VADD(yp, py.x, py.y);
;                     } else {
;                         VPKMUL(px, P01, Rkk[c][0].xy); VPKFMA(px, P23, Rkk[c][0].zw, px); VPKFMA(px, P45, Rkk[c][1].xy, px); VPKFMA(px, P67, Rkk[c][1].zw, px);
;                         VADD(x, px.x, px.y);
;                     }
;                     asm volatile("" ::: "memory");
;                     if (s + 1 < 32) LOADREC((s + 1) & 1, s + 1);
;                     asm volatile("" ::: "memory");
;                     VPKMULBL(t01, vv2, Rkm[c][0].xy); VPKMULBL(t23, vv2, Rkm[c][0].zw);
;                     VDPP1(x); if (s >= 1) VDPP1(yp);
;                     VPKMULBL(t45, vv2, Rkm[c][1].xy); VPKMULBL(t67, vv2, Rkm[c][1].zw);
;                     VDPP2(x); if (s >= 1) VDPP2(yp);
;                     VPKFMA(P01, P01, Rw[c][0].xy, t01); VPKFMA(P23, P23, Rw[c][0].zw, t23);
;                     VDPP3(x); if (s >= 1) VDPP3(yp);
;                     VPKFMA(P45, P45, Rw[c][1].xy, t45); VPKFMA(P67, P67, Rw[c][1].zw, t67);
;                     if (s >= 1) { if (s - 1 < 8) YSHIFT(yk0); else if (s - 1 < 16) YSHIFT(yk1); else if (s - 1 < 24) YSHIFT(yk2); else YSHIFT(yk3); }
;                     x = x * si;
;                     f32x2 x2; x2.x = x; asm volatile("" : "+v"(x2));
;                     VPKNFMABL(P01, x2, Rka[c][0].xy, P01); VPKNFMABL(P23, x2, Rka[c][0].zw, P23); VPKNFMABL(P45, x2, Rka[c][1].xy, P45); VPKNFMABL(P67, x2, Rka[c][1].zw, P67);
;                 }
	ds_read_b128 v[64:67], v35 offset:2448
	ds_read_b128 v[76:79], v35 offset:28560
	ds_read_b32 v94, v36 offset:1152
	ds_read_b32 v95, v38 offset:1152
	ds_read_b128 v[68:71], v35 offset:11152
	ds_read_b128 v[72:75], v35 offset:19856
	ds_read_b128 v[80:83], v35 offset:37264
	v_pk_mul_f32 v[8:9], v[0:1], v[48:49] op_sel_hi:[1,0]
	v_pk_mul_f32 v[10:11], v[0:1], v[84:85] op_sel_hi:[1,0]
	v_pk_fma_f32 v[8:9], v[2:3], v[48:49], v[8:9] op_sel:[0,1,0] op_sel_hi:[1,1,1]
	v_pk_fma_f32 v[10:11], v[2:3], v[84:85], v[10:11] op_sel:[0,1,0] op_sel_hi:[1,1,1]
	v_pk_fma_f32 v[8:9], v[4:5], v[50:51], v[8:9] op_sel_hi:[1,0,1]
	v_pk_fma_f32 v[10:11], v[4:5], v[86:87], v[10:11] op_sel_hi:[1,0,1]
	v_pk_fma_f32 v[8:9], v[6:7], v[50:51], v[8:9] op_sel:[0,1,0] op_sel_hi:[1,1,1]
	v_pk_fma_f32 v[10:11], v[6:7], v[86:87], v[10:11] op_sel:[0,1,0] op_sel_hi:[1,1,1]
	v_readlane_b32 s10, v34, 8
	v_pk_mul_f32 v[16:17], v[92:93], v[60:61] op_sel_hi:[1,0]
	v_pk_mul_f32 v[18:19], v[92:93], v[60:61] op_sel:[0,1] op_sel_hi:[1,1]
	v_add_f32_dpp v8, v9, v8 quad_perm:[1,0,3,2] row_mask:0xf bank_mask:0xf bound_ctrl:1
	v_add_f32_dpp v10, v11, v10 quad_perm:[1,0,3,2] row_mask:0xf bank_mask:0xf bound_ctrl:1
	v_pk_mul_f32 v[20:21], v[92:93], v[62:63] op_sel_hi:[1,0]
	v_pk_mul_f32 v[22:23], v[92:93], v[62:63] op_sel:[0,1] op_sel_hi:[1,1]
	v_add_f32_dpp v8, v8, v8 quad_perm:[2,3,0,1] row_mask:0xf bank_mask:0xf bound_ctrl:1
	v_add_f32_dpp v10, v10, v10 quad_perm:[2,3,0,1] row_mask:0xf bank_mask:0xf bound_ctrl:1
	v_pk_fma_f32 v[0:1], v[0:1], v[52:53], v[16:17] op_sel_hi:[1,0,1]
	v_pk_fma_f32 v[2:3], v[2:3], v[52:53], v[18:19] op_sel:[0,1,0] op_sel_hi:[1,1,1]
	v_add_f32_dpp v8, v8, v8 row_ror:4 row_mask:0xf bank_mask:0xf bound_ctrl:1
	v_add_f32_dpp v10, v10, v10 row_ror:4 row_mask:0xf bank_mask:0xf bound_ctrl:1
	v_pk_fma_f32 v[4:5], v[4:5], v[54:55], v[20:21] op_sel_hi:[1,0,1]
	v_add_f32_dpp v8, v8, v8 row_ror:8 row_mask:0xf bank_mask:0xf bound_ctrl:1
	v_mul_f32_e32 v8, s10, v8
	v_add_f32_dpp v97, v10, v10 row_ror:8 row_mask:0xf bank_mask:0x8 bound_ctrl:1
	v_pk_fma_f32 v[6:7], v[6:7], v[54:55], v[22:23] op_sel:[0,1,0] op_sel_hi:[1,1,1]
	v_mov_b32_dpp v9, v8 quad_perm:[1,0,3,2] row_mask:0xf bank_mask:0xf
	v_pk_fma_f32 v[0:1], v[8:9], v[56:57], v[0:1] op_sel_hi:[1,0,1] neg_lo:[1,0,0] neg_hi:[1,0,0]
	v_pk_fma_f32 v[2:3], v[8:9], v[56:57], v[2:3] op_sel:[0,1,0] op_sel_hi:[1,1,1] neg_lo:[1,0,0] neg_hi:[1,0,0]
	v_pk_fma_f32 v[4:5], v[8:9], v[58:59], v[4:5] op_sel_hi:[1,0,1] neg_lo:[1,0,0] neg_hi:[1,0,0]
	v_pk_fma_f32 v[6:7], v[8:9], v[58:59], v[6:7] op_sel:[0,1,0] op_sel_hi:[1,1,1] neg_lo:[1,0,0] neg_hi:[1,0,0]
	s_waitcnt lgkmcnt(0)
	ds_read_b128 v[48:51], v35 offset:2720
	ds_read_b128 v[60:63], v35 offset:28832
	ds_read_b32 v92, v36 offset:1280
	ds_read_b32 v93, v38 offset:1280
	ds_read_b128 v[52:55], v35 offset:11424
	ds_read_b128 v[56:59], v35 offset:20128
	ds_read_b128 v[84:87], v35 offset:37536
	v_pk_mul_f32 v[8:9], v[0:1], v[64:65] op_sel_hi:[1,0]
	v_pk_mul_f32 v[10:11], v[0:1], v[88:89] op_sel_hi:[1,0]
	v_pk_fma_f32 v[8:9], v[2:3], v[64:65], v[8:9] op_sel:[0,1,0] op_sel_hi:[1,1,1]
	v_pk_fma_f32 v[10:11], v[2:3], v[88:89], v[10:11] op_sel:[0,1,0] op_sel_hi:[1,1,1]
	v_pk_fma_f32 v[8:9], v[4:5], v[66:67], v[8:9] op_sel_hi:[1,0,1]
	v_pk_fma_f32 v[10:11], v[4:5], v[90:91], v[10:11] op_sel_hi:[1,0,1]
	v_pk_fma_f32 v[8:9], v[6:7], v[66:67], v[8:9] op_sel:[0,1,0] op_sel_hi:[1,1,1]
	v_pk_fma_f32 v[10:11], v[6:7], v[90:91], v[10:11] op_sel:[0,1,0] op_sel_hi:[1,1,1]
	v_readlane_b32 s10, v34, 9
	v_pk_mul_f32 v[16:17], v[94:95], v[76:77] op_sel_hi:[1,0]
	v_pk_mul_f32 v[18:19], v[94:95], v[76:77] op_sel:[0,1] op_sel_hi:[1,1]
	v_add_f32_dpp v8, v9, v8 quad_perm:[1,0,3,2] row_mask:0xf bank_mask:0xf bound_ctrl:1
	v_add_f32_dpp v10, v11, v10 quad_perm:[1,0,3,2] row_mask:0xf bank_mask:0xf bound_ctrl:1
	v_pk_mul_f32 v[20:21], v[94:95], v[78:79] op_sel_hi:[1,0]
	v_pk_mul_f32 v[22:23], v[94:95], v[78:79] op_sel:[0,1] op_sel_hi:[1,1]
	v_add_f32_dpp v8, v8, v8 quad_perm:[2,3,0,1] row_mask:0xf bank_mask:0xf bound_ctrl:1
	v_add_f32_dpp v10, v10, v10 quad_perm:[2,3,0,1] row_mask:0xf bank_mask:0xf bound_ctrl:1
	v_pk_fma_f32 v[0:1], v[0:1], v[68:69], v[16:17] op_sel_hi:[1,0,1]
	v_pk_fma_f32 v[2:3], v[2:3], v[68:69], v[18:19] op_sel:[0,1,0] op_sel_hi:[1,1,1]
	v_add_f32_dpp v8, v8, v8 row_ror:4 row_mask:0xf bank_mask:0xf bound_ctrl:1
	v_add_f32_dpp v10, v10, v10 row_ror:4 row_mask:0xf bank_mask:0xf bound_ctrl:1
	v_pk_fma_f32 v[4:5], v[4:5], v[70:71], v[20:21] op_sel_hi:[1,0,1]
	v_add_f32_dpp v8, v8, v8 row_ror:8 row_mask:0xf bank_mask:0xf bound_ctrl:1
	v_mul_f32_e32 v8, s10, v8
	v_add_f32_dpp v98, v10, v10 row_ror:8 row_mask:0xf bank_mask:0x1 bound_ctrl:1
	v_pk_fma_f32 v[6:7], v[6:7], v[70:71], v[22:23] op_sel:[0,1,0] op_sel_hi:[1,1,1]
	v_mov_b32_dpp v9, v8 quad_perm:[1,0,3,2] row_mask:0xf bank_mask:0xf
	v_pk_fma_f32 v[0:1], v[8:9], v[72:73], v[0:1] op_sel_hi:[1,0,1] neg_lo:[1,0,0] neg_hi:[1,0,0]
	v_pk_fma_f32 v[2:3], v[8:9], v[72:73], v[2:3] op_sel:[0,1,0] op_sel_hi:[1,1,1] neg_lo:[1,0,0] neg_hi:[1,0,0]
	v_pk_fma_f32 v[4:5], v[8:9], v[74:75], v[4:5] op_sel_hi:[1,0,1] neg_lo:[1,0,0] neg_hi:[1,0,0]
	v_pk_fma_f32 v[6:7], v[8:9], v[74:75], v[6:7] op_sel:[0,1,0] op_sel_hi:[1,1,1] neg_lo:[1,0,0] neg_hi:[1,0,0]
	s_waitcnt lgkmcnt(0)
; #define VPKMUL(d, a, b) asm volatile("v_pk_mul_f32 %0, %1, %2" : "=v"(d) : "v"(a), "v"(b))
; __device__ __forceinline__ void scan_half(const Params& p, LAS unsigned char* lds, int pi, int rh, int pass) {
;     ...
;                 LOADREC(0, 0);
;                 float yp = 0.f, yk0 = 0.f, yk1 = 0.f, yk2 = 0.f, yk3 = 0.f;
;     ...
; #pragma unroll
;                 for (int s = 0; s < 32; ++s) {
;                     const int c = s & 1, pc = c ^ 1;
;                     const float si = __int_as_float(__builtin_amdgcn_readlane(__float_as_int(inv2), s));
;                     f32x2 px, py, t01, t23, t45, t67; float x;
;                     f32x2 vv2; vv2.x = Rv[c]; asm volatile("" : "+v"(vv2));
;                     if (s >= 1) {
;                         VPKMUL(px, P01, Rkk[c][0].xy); VPKMUL(py, P01, Rr[pc][0].xy); VPKFMA(px, P23, Rkk[c][0].zw, px); VPKFMA(py, P23, Rr[pc][0].zw, py);
;                         VPKFMA(px, P45, Rkk[c][1].xy, px); VPKFMA(py, P45, Rr[pc][1].xy, py); VPKFMA(px, P67, Rkk[c][1].zw, px); VPKFMA(py, P67, Rr[pc][1].zw, py);
;                         VADD(x, px.x, px.y); VADD(yp, py.x, py.y);
;                     } else {
;                         VPKMUL(px, P01, Rkk[c][0].xy); VPKFMA(px, P23, Rkk[c][0].zw, px); VPKFMA(px, P45, Rkk[c][1].xy, px); VPKFMA(px, P67, Rkk[c][1].zw, px);
;                         VADD(x, px.x, px.y);
;                     }
;                     asm volatile("" ::: "memory");
;                     if (s + 1 < 32) LOADREC((s + 1) & 1, s + 1);
;                     asm volatile("" ::: "memory");
;                     VPKMULBL(t01, vv2, Rkm[c][0].xy); VPKMULBL(t23, vv2, Rkm[c][0].zw);
;                     VDPP1(x); if (s >= 1) VDPP1(yp);
;                     VPKMULBL(t45, vv2, Rkm[c][1].xy); VPKMULBL(t67, vv2, Rkm[c][1].zw);
;                     VDPP2(x); if (s >= 1) VDPP2(yp);
;                     VPKFMA(P01, P01, Rw[c][0].xy, t01); VPKFMA(P23, P23, Rw[c][0].zw, t23);
;                     VDPP3(x); if (s >= 1) VDPP3(yp);
;                     VPKFMA(P45, P45, Rw[c][1].xy, t45); VPKFMA(P67, P67, Rw[c][1].zw, t67);
;                     if (s >= 1) { if (s - 1 < 8) YSHIFT(yk0); else if (s - 1 < 16) YSHIFT(yk1); else if (s - 1 < 24) YSHIFT(yk2); else YSHIFT(yk3); }
;                     x = x * si;
;                     f32x2 x2; x2.x = x; asm volatile("" : "+v"(x2));
	ds_read_b128 v[64:67], v35 offset:2992
	ds_read_b128 v[76:79], v35 offset:29104
	ds_read_b32 v94, v36 offset:1408
	ds_read_b32 v95, v38 offset:1408
	ds_read_b128 v[68:71], v35 offset:11696
	ds_read_b128 v[72:75], v35 offset:20400
	ds_read_b128 v[88:91], v35 offset:37808
	v_pk_mul_f32 v[8:9], v[0:1], v[48:49] op_sel_hi:[1,0]
	v_pk_mul_f32 v[10:11], v[0:1], v[80:81] op_sel_hi:[1,0]
	v_pk_fma_f32 v[8:9], v[2:3], v[48:49], v[8:9] op_sel:[0,1,0] op_sel_hi:[1,1,1]
	v_pk_fma_f32 v[10:11], v[2:3], v[80:81], v[10:11] op_sel:[0,1,0] op_sel_hi:[1,1,1]
	v_pk_fma_f32 v[8:9], v[4:5], v[50:51], v[8:9] op_sel_hi:[1,0,1]
	v_pk_fma_f32 v[10:11], v[4:5], v[82:83], v[10:11] op_sel_hi:[1,0,1]
	v_pk_fma_f32 v[8:9], v[6:7], v[50:51], v[8:9] op_sel:[0,1,0] op_sel_hi:[1,1,1]
	v_pk_fma_f32 v[10:11], v[6:7], v[82:83], v[10:11] op_sel:[0,1,0] op_sel_hi:[1,1,1]
	v_readlane_b32 s10, v34, 10
	v_pk_mul_f32 v[16:17], v[92:93], v[60:61] op_sel_hi:[1,0]
	v_pk_mul_f32 v[18:19], v[92:93], v[60:61] op_sel:[0,1] op_sel_hi:[1,1]
	v_add_f32_dpp v8, v9, v8 quad_perm:[1,0,3,2] row_mask:0xf bank_mask:0xf bound_ctrl:1
	v_add_f32_dpp v10, v11, v10 quad_perm:[1,0,3,2] row_mask:0xf bank_mask:0xf bound_ctrl:1
	v_pk_mul_f32 v[20:21], v[92:93], v[62:63] op_sel_hi:[1,0]
	v_pk_mul_f32 v[22:23], v[92:93], v[62:63] op_sel:[0,1] op_sel_hi:[1,1]
	v_add_f32_dpp v8, v8, v8 quad_perm:[2,3,0,1] row_mask:0xf bank_mask:0xf bound_ctrl:1
	v_add_f32_dpp v10, v10, v10 quad_perm:[2,3,0,1] row_mask:0xf bank_mask:0xf bound_ctrl:1
	v_pk_fma_f32 v[0:1], v[0:1], v[52:53], v[16:17] op_sel_hi:[1,0,1]
	v_pk_fma_f32 v[2:3], v[2:3], v[52:53], v[18:19] op_sel:[0,1,0] op_sel_hi:[1,1,1]
	v_add_f32_dpp v8, v8, v8 row_ror:4 row_mask:0xf bank_mask:0xf bound_ctrl:1
	v_add_f32_dpp v10, v10, v10 row_ror:4 row_mask:0xf bank_mask:0xf bound_ctrl:1
	v_pk_fma_f32 v[4:5], v[4:5], v[54:55], v[20:21] op_sel_hi:[1,0,1]
	v_add_f32_dpp v8, v8, v8 row_ror:8 row_mask:0xf bank_mask:0xf bound_ctrl:1
	v_mul_f32_e32 v8, s10, v8
	v_add_f32_dpp v98, v10, v10 row_ror:8 row_mask:0xf bank_mask:0x2 bound_ctrl:1
	v_pk_fma_f32 v[6:7], v[6:7], v[54:55], v[22:23] op_sel:[0,1,0] op_sel_hi:[1,1,1]
	v_mov_b32_dpp v9, v8 quad_perm:[1,0,3,2] row_mask:0xf bank_mask:0xf
	v_pk_fma_f32 v[0:1], v[8:9], v[56:57], v[0:1] op_sel_hi:[1,0,1] neg_lo:[1,0,0] neg_hi:[1,0,0]
	v_pk_fma_f32 v[2:3], v[8:9], v[56:57], v[2:3] op_sel:[0,1,0] op_sel_hi:[1,1,1] neg_lo:[1,0,0] neg_hi:[1,0,0]
	v_pk_fma_f32 v[4:5], v[8:9], v[58:59], v[4:5] op_sel_hi:[1,0,1] neg_lo:[1,0,0] neg_hi:[1,0,0]
	v_pk_fma_f32 v[6:7], v[8:9], v[58:59], v[6:7] op_sel:[0,1,0] op_sel_hi:[1,1,1] neg_lo:[1,0,0] neg_hi:[1,0,0]
	s_waitcnt lgkmcnt(0)
	ds_read_b128 v[48:51], v35 offset:3264
	ds_read_b128 v[60:63], v35 offset:29376
	ds_read_b32 v92, v36 offset:1536
	ds_read_b32 v93, v38 offset:1536
	ds_read_b128 v[52:55], v35 offset:11968
	ds_read_b128 v[56:59], v35 offset:20672
	ds_read_b128 v[80:83], v35 offset:38080
	v_pk_mul_f32 v[8:9], v[0:1], v[64:65] op_sel_hi:[1,0]
	v_pk_mul_f32 v[10:11], v[0:1], v[84:85] op_sel_hi:[1,0]
	v_pk_fma_f32 v[8:9], v[2:3], v[64:65], v[8:9] op_sel:[0,1,0] op_sel_hi:[1,1,1]
	v_pk_fma_f32 v[10:11], v[2:3], v[84:85], v[10:11] op_sel:[0,1,0] op_sel_hi:[1,1,1]
	v_pk_fma_f32 v[8:9], v[4:5], v[66:67], v[8:9] op_sel_hi:[1,0,1]
	v_pk_fma_f32 v[10:11], v[4:5], v[86:87], v[10:11] op_sel_hi:[1,0,1]
	v_pk_fma_f32 v[8:9], v[6:7], v[66:67], v[8:9] op_sel:[0,1,0] op_sel_hi:[1,1,1]
	v_pk_fma_f32 v[10:11], v[6:7], v[86:87], v[10:11] op_sel:[0,1,0] op_sel_hi:[1,1,1]
	v_readlane_b32 s10, v34, 11
	v_pk_mul_f32 v[16:17], v[94:95], v[76:77] op_sel_hi:[1,0]
	v_pk_mul_f32 v[18:19], v[94:95], v[76:77] op_sel:[0,1] op_sel_hi:[1,1]
	v_add_f32_dpp v8, v9, v8 quad_perm:[1,0,3,2] row_mask:0xf bank_mask:0xf bound_ctrl:1
	v_add_f32_dpp v10, v11, v10 quad_perm:[1,0,3,2] row_mask:0xf bank_mask:0xf bound_ctrl:1
	v_pk_mul_f32 v[20:21], v[94:95], v[78:79] op_sel_hi:[1,0]
	v_pk_mul_f32 v[22:23], v[94:95], v[78:79] op_sel:[0,1] op_sel_hi:[1,1]
	v_add_f32_dpp v8, v8, v8 quad_perm:[2,3,0,1] row_mask:0xf bank_mask:0xf bound_ctrl:1
	v_add_f32_dpp v10, v10, v10 quad_perm:[2,3,0,1] row_mask:0xf bank_mask:0xf bound_ctrl:1
	v_pk_fma_f32 v[0:1], v[0:1], v[68:69], v[16:17] op_sel_hi:[1,0,1]
	v_pk_fma_f32 v[2:3], v[2:3], v[68:69], v[18:19] op_sel:[0,1,0] op_sel_hi:[1,1,1]
	v_add_f32_dpp v8, v8, v8 row_ror:4 row_mask:0xf bank_mask:0xf bound_ctrl:1
	v_add_f32_dpp v10, v10, v10 row_ror:4 row_mask:0xf bank_mask:0xf bound_ctrl:1
	v_pk_fma_f32 v[4:5], v[4:5], v[70:71], v[20:21] op_sel_hi:[1,0,1]
	v_add_f32_dpp v8, v8, v8 row_ror:8 row_mask:0xf bank_mask:0xf bound_ctrl:1
	v_mul_f32_e32 v8, s10, v8
	v_add_f32_dpp v98, v10, v10 row_ror:8 row_mask:0xf bank_mask:0x4 bound_ctrl:1
	v_pk_fma_f32 v[6:7], v[6:7], v[70:71], v[22:23] op_sel:[0,1,0] op_sel_hi:[1,1,1]
	v_mov_b32_dpp v9, v8 quad_perm:[1,0,3,2] row_mask:0xf bank_mask:0xf
	v_pk_fma_f32 v[0:1], v[8:9], v[72:73], v[0:1] op_sel_hi:[1,0,1] neg_lo:[1,0,0] neg_hi:[1,0,0]
	v_pk_fma_f32 v[2:3], v[8:9], v[72:73], v[2:3] op_sel:[0,1,0] op_sel_hi:[1,1,1] neg_lo:[1,0,0] neg_hi:[1,0,0]
	v_pk_fma_f32 v[4:5], v[8:9], v[74:75], v[4:5] op_sel_hi:[1,0,1] neg_lo:[1,0,0] neg_hi:[1,0,0]
	v_pk_fma_f32 v[6:7], v[8:9], v[74:75], v[6:7] op_sel:[0,1,0] op_sel_hi:[1,1,1] neg_lo:[1,0,0] neg_hi:[1,0,0]
	s_waitcnt lgkmcnt(0)
; #define VPKMUL(d, a, b) asm volatile("v_pk_mul_f32 %0, %1, %2" : "=v"(d) : "v"(a), "v"(b))
; __device__ __forceinline__ void scan_half(const Params& p, LAS unsigned char* lds, int pi, int rh, int pass) {
;     ...
;                 LOADREC(0, 0);
;                 float yp = 0.f, yk0 = 0.f, yk1 = 0.f, yk2 = 0.f, yk3 = 0.f;
;     ...
; #pragma unroll
;                 for (int s = 0; s < 32; ++s) {
;                     const int c = s & 1, pc = c ^ 1;
;                     const float si = __int_as_float(__builtin_amdgcn_readlane(__float_as_int(inv2), s));
;                     f32x2 px, py, t01, t23, t45, t67; float x;
;                     f32x2 vv2; vv2.x = Rv[c]; asm volatile("" : "+v"(vv2));
;                     if (s >= 1) {
;                         VPKMUL(px, P01, Rkk[c][0].xy); VPKMUL(py, P01, Rr[pc][0].xy); VPKFMA(px, P23, Rkk[c][0].zw, px); VPKFMA(py, P23, Rr[pc][0].zw, py);
;                         VPKFMA(px, P45, Rkk[c][1].xy, px); VPKFMA(py, P45, Rr[pc][1].xy, py); VPKFMA(px, P67, Rkk[c][1].zw, px); VPKFMA(py, P67, Rr[pc][1].zw, py);
;                         VADD(x, px.x, px.y); VADD(yp, py.x, py.y);
;                     } else {
;                         VPKMUL(px, P01, Rkk[c][0].xy); VPKFMA(px, P23, Rkk[c][0].zw, px); VPKFMA(px, P45, Rkk[c][1].xy, px); VPKFMA(px, P67, Rkk[c][1].zw, px);
;                         VADD(x, px.x, px.y);
;                     }
;                     asm volatile("" ::: "memory");
;                     if (s + 1 < 32) LOADREC((s + 1) & 1, s + 1);
;                     asm volatile("" ::: "memory");
;                     VPKMULBL(t01, vv2, Rkm[c][0].xy); VPKMULBL(t23, vv2, Rkm[c][0].zw);
;                     VDPP1(x); if (s >= 1) VDPP1(yp);
;                     VPKMULBL(t45, vv2, Rkm[c][1].xy); VPKMULBL(t67, vv2, Rkm[c][1].zw);
;                     VDPP2(x); if (s >= 1) VDPP2(yp);
;                     VPKFMA(P01, P01, Rw[c][0].xy, t01); VPKFMA(P23, P23, Rw[c][0].zw, t23);
;                     VDPP3(x); if (s >= 1) VDPP3(yp);
;                     VPKFMA(P45, P45, Rw[c][1].xy, t45); VPKFMA(P67, P67, Rw[c][1].zw, t67);
;                     if (s >= 1) { if (s - 1 < 8) YSHIFT(yk0); else if (s - 1 < 16) YSHIFT(yk1); else if (s - 1 < 24) YSHIFT(yk2); else YSHIFT(yk3); }
;                     x = x * si;
;                     f32x2 x2; x2.x = x; asm volatile("" : "+v"(x2));
	ds_read_b128 v[64:67], v35 offset:3536
	ds_read_b128 v[76:79], v35 offset:29648
	ds_read_b32 v94, v36 offset:1664
	ds_read_b32 v95, v38 offset:1664
	ds_read_b128 v[68:71], v35 offset:12240
	ds_read_b128 v[72:75], v35 offset:20944
	ds_read_b128 v[84:87], v35 offset:38352
	v_pk_mul_f32 v[8:9], v[0:1], v[48:49] op_sel_hi:[1,0]
	v_pk_mul_f32 v[10:11], v[0:1], v[88:89] op_sel_hi:[1,0]
	v_pk_fma_f32 v[8:9], v[2:3], v[48:49], v[8:9] op_sel:[0,1,0] op_sel_hi:[1,1,1]
	v_pk_fma_f32 v[10:11], v[2:3], v[88:89], v[10:11] op_sel:[0,1,0] op_sel_hi:[1,1,1]
	v_pk_fma_f32 v[8:9], v[4:5], v[50:51], v[8:9] op_sel_hi:[1,0,1]
	v_pk_fma_f32 v[10:11], v[4:5], v[90:91], v[10:11] op_sel_hi:[1,0,1]
	v_pk_fma_f32 v[8:9], v[6:7], v[50:51], v[8:9] op_sel:[0,1,0] op_sel_hi:[1,1,1]
	v_pk_fma_f32 v[10:11], v[6:7], v[90:91], v[10:11] op_sel:[0,1,0] op_sel_hi:[1,1,1]
	v_readlane_b32 s10, v34, 12
	v_pk_mul_f32 v[16:17], v[92:93], v[60:61] op_sel_hi:[1,0]
	v_pk_mul_f32 v[18:19], v[92:93], v[60:61] op_sel:[0,1] op_sel_hi:[1,1]
	v_add_f32_dpp v8, v9, v8 quad_perm:[1,0,3,2] row_mask:0xf bank_mask:0xf bound_ctrl:1
	v_add_f32_dpp v10, v11, v10 quad_perm:[1,0,3,2] row_mask:0xf bank_mask:0xf bound_ctrl:1
	v_pk_mul_f32 v[20:21], v[92:93], v[62:63] op_sel_hi:[1,0]
	v_pk_mul_f32 v[22:23], v[92:93], v[62:63] op_sel:[0,1] op_sel_hi:[1,1]
	v_add_f32_dpp v8, v8, v8 quad_perm:[2,3,0,1] row_mask:0xf bank_mask:0xf bound_ctrl:1
	v_add_f32_dpp v10, v10, v10 quad_perm:[2,3,0,1] row_mask:0xf bank_mask:0xf bound_ctrl:1
	v_pk_fma_f32 v[0:1], v[0:1], v[52:53], v[16:17] op_sel_hi:[1,0,1]
	v_pk_fma_f32 v[2:3], v[2:3], v[52:53], v[18:19] op_sel:[0,1,0] op_sel_hi:[1,1,1]
	v_add_f32_dpp v8, v8, v8 row_ror:4 row_mask:0xf bank_mask:0xf bound_ctrl:1
	v_add_f32_dpp v10, v10, v10 row_ror:4 row_mask:0xf bank_mask:0xf bound_ctrl:1
	v_pk_fma_f32 v[4:5], v[4:5], v[54:55], v[20:21] op_sel_hi:[1,0,1]
	v_add_f32_dpp v8, v8, v8 row_ror:8 row_mask:0xf bank_mask:0xf bound_ctrl:1
	v_mul_f32_e32 v8, s10, v8
	v_add_f32_dpp v98, v10, v10 row_ror:8 row_mask:0xf bank_mask:0x8 bound_ctrl:1
	v_pk_fma_f32 v[6:7], v[6:7], v[54:55], v[22:23] op_sel:[0,1,0] op_sel_hi:[1,1,1]
	v_mov_b32_dpp v9, v8 quad_perm:[1,0,3,2] row_mask:0xf bank_mask:0xf
	v_pk_fma_f32 v[0:1], v[8:9], v[56:57], v[0:1] op_sel_hi:[1,0,1] neg_lo:[1,0,0] neg_hi:[1,0,0]
	v_pk_fma_f32 v[2:3], v[8:9], v[56:57], v[2:3] op_sel:[0,1,0] op_sel_hi:[1,1,1] neg_lo:[1,0,0] neg_hi:[1,0,0]
	v_pk_fma_f32 v[4:5], v[8:9], v[58:59], v[4:5] op_sel_hi:[1,0,1] neg_lo:[1,0,0] neg_hi:[1,0,0]
	v_pk_fma_f32 v[6:7], v[8:9], v[58:59], v[6:7] op_sel:[0,1,0] op_sel_hi:[1,1,1] neg_lo:[1,0,0] neg_hi:[1,0,0]
	s_waitcnt lgkmcnt(0)
	ds_read_b128 v[48:51], v35 offset:3808
	ds_read_b128 v[60:63], v35 offset:29920
	ds_read_b32 v92, v36 offset:1792
	ds_read_b32 v93, v38 offset:1792
	ds_read_b128 v[52:55], v35 offset:12512
	ds_read_b128 v[56:59], v35 offset:21216
	ds_read_b128 v[88:91], v35 offset:38624
	v_pk_mul_f32 v[8:9], v[0:1], v[64:65] op_sel_hi:[1,0]
	v_pk_mul_f32 v[10:11], v[0:1], v[80:81] op_sel_hi:[1,0]
	v_pk_fma_f32 v[8:9], v[2:3], v[64:65], v[8:9] op_sel:[0,1,0] op_sel_hi:[1,1,1]
	v_pk_fma_f32 v[10:11], v[2:3], v[80:81], v[10:11] op_sel:[0,1,0] op_sel_hi:[1,1,1]
	v_pk_fma_f32 v[8:9], v[4:5], v[66:67], v[8:9] op_sel_hi:[1,0,1]
	v_pk_fma_f32 v[10:11], v[4:5], v[82:83], v[10:11] op_sel_hi:[1,0,1]
	v_pk_fma_f32 v[8:9], v[6:7], v[66:67], v[8:9] op_sel:[0,1,0] op_sel_hi:[1,1,1]
	v_pk_fma_f32 v[10:11], v[6:7], v[82:83], v[10:11] op_sel:[0,1,0] op_sel_hi:[1,1,1]
	v_readlane_b32 s10, v34, 13
	v_pk_mul_f32 v[16:17], v[94:95], v[76:77] op_sel_hi:[1,0]
	v_pk_mul_f32 v[18:19], v[94:95], v[76:77] op_sel:[0,1] op_sel_hi:[1,1]
	v_add_f32_dpp v8, v9, v8 quad_perm:[1,0,3,2] row_mask:0xf bank_mask:0xf bound_ctrl:1
	v_add_f32_dpp v10, v11, v10 quad_perm:[1,0,3,2] row_mask:0xf bank_mask:0xf bound_ctrl:1
	v_pk_mul_f32 v[20:21], v[94:95], v[78:79] op_sel_hi:[1,0]
	v_pk_mul_f32 v[22:23], v[94:95], v[78:79] op_sel:[0,1] op_sel_hi:[1,1]
	v_add_f32_dpp v8, v8, v8 quad_perm:[2,3,0,1] row_mask:0xf bank_mask:0xf bound_ctrl:1
	v_add_f32_dpp v10, v10, v10 quad_perm:[2,3,0,1] row_mask:0xf bank_mask:0xf bound_ctrl:1
	v_pk_fma_f32 v[0:1], v[0:1], v[68:69], v[16:17] op_sel_hi:[1,0,1]
	v_pk_fma_f32 v[2:3], v[2:3], v[68:69], v[18:19] op_sel:[0,1,0] op_sel_hi:[1,1,1]
	v_add_f32_dpp v8, v8, v8 row_ror:4 row_mask:0xf bank_mask:0xf bound_ctrl:1
	v_add_f32_dpp v10, v10, v10 row_ror:4 row_mask:0xf bank_mask:0xf bound_ctrl:1
	v_pk_fma_f32 v[4:5], v[4:5], v[70:71], v[20:21] op_sel_hi:[1,0,1]
	v_add_f32_dpp v8, v8, v8 row_ror:8 row_mask:0xf bank_mask:0xf bound_ctrl:1
	v_mul_f32_e32 v8, s10, v8
	v_add_f32_dpp v99, v10, v10 row_ror:8 row_mask:0xf bank_mask:0x1 bound_ctrl:1
	v_pk_fma_f32 v[6:7], v[6:7], v[70:71], v[22:23] op_sel:[0,1,0] op_sel_hi:[1,1,1]
	v_mov_b32_dpp v9, v8 quad_perm:[1,0,3,2] row_mask:0xf bank_mask:0xf
	v_pk_fma_f32 v[0:1], v[8:9], v[72:73], v[0:1] op_sel_hi:[1,0,1] neg_lo:[1,0,0] neg_hi:[1,0,0]
	v_pk_fma_f32 v[2:3], v[8:9], v[72:73], v[2:3] op_sel:[0,1,0] op_sel_hi:[1,1,1] neg_lo:[1,0,0] neg_hi:[1,0,0]
	v_pk_fma_f32 v[4:5], v[8:9], v[74:75], v[4:5] op_sel_hi:[1,0,1] neg_lo:[1,0,0] neg_hi:[1,0,0]
	v_pk_fma_f32 v[6:7], v[8:9], v[74:75], v[6:7] op_sel:[0,1,0] op_sel_hi:[1,1,1] neg_lo:[1,0,0] neg_hi:[1,0,0]
	s_waitcnt lgkmcnt(0)
; #define VPKMUL(d, a, b) asm volatile("v_pk_mul_f32 %0, %1, %2" : "=v"(d) : "v"(a), "v"(b))
; __device__ __forceinline__ void scan_half(const Params& p, LAS unsigned char* lds, int pi, int rh, int pass) {
;     ...
;                 LOADREC(0, 0);
;                 float yp = 0.f, yk0 = 0.f, yk1 = 0.f, yk2 = 0.f, yk3 = 0.f;
;     ...
; #pragma unroll
;                 for (int s = 0; s < 32; ++s) {
;                     const int c = s & 1, pc = c ^ 1;
;                     const float si = __int_as_float(__builtin_amdgcn_readlane(__float_as_int(inv2), s));
;                     f32x2 px, py, t01, t23, t45, t67; float x;
;                     f32x2 vv2; vv2.x = Rv[c]; asm volatile("" : "+v"(vv2));
;                     if (s >= 1) {
;                         VPKMUL(px, P01, Rkk[c][0].xy); VPKMUL(py, P01, Rr[pc][0].xy); VPKFMA(px, P23, Rkk[c][0].zw, px); VPKFMA(py, P23, Rr[pc][0].zw, py);
;                         VPKFMA(px, P45, Rkk[c][1].xy, px); VPKFMA(py, P45, Rr[pc][1].xy, py); VPKFMA(px, P67, Rkk[c][1].zw, px); VPKFMA(py, P67, Rr[pc][1].zw, py);
;                         VADD(x, px.x, px.y); VADD(yp, py.x, py.y);
;                     } else {
;                         VPKMUL(px, P01, Rkk[c][0].xy); VPKFMA(px, P23, Rkk[c][0].zw, px); VPKFMA(px, P45, Rkk[c][1].xy, px); VPKFMA(px, P67, Rkk[c][1].zw, px);
;                         VADD(x, px.x, px.y);
;                     }
;                     asm volatile("" ::: "memory");
;                     if (s + 1 < 32) LOADREC((s + 1) & 1, s + 1);
;                     asm volatile("" ::: "memory");
;                     VPKMULBL(t01, vv2, Rkm[c][0].xy); VPKMULBL(t23, vv2, Rkm[c][0].zw);
;                     VDPP1(x); if (s >= 1) VDPP1(yp);
;                     VPKMULBL(t45, vv2, Rkm[c][1].xy); VPKMULBL(t67, vv2, Rkm[c][1].zw);
;                     VDPP2(x); if (s >= 1) VDPP2(yp);
;                     VPKFMA(P01, P01, Rw[c][0].xy, t01); VPKFMA(P23, P23, Rw[c][0].zw, t23);
;                     VDPP3(x); if (s >= 1) VDPP3(yp);
;                     VPKFMA(P45, P45, Rw[c][1].xy, t45); VPKFMA(P67, P67, Rw[c][1].zw, t67);
;                     if (s >= 1) { if (s - 1 < 8) YSHIFT(yk0); else if (s - 1 < 16) YSHIFT(yk1); else if (s - 1 < 24) YSHIFT(yk2); else YSHIFT(yk3); }
;                     x = x * si;
;                     f32x2 x2; x2.x = x; asm volatile("" : "+v"(x2));
	ds_read_b128 v[64:67], v35 offset:4080
	ds_read_b128 v[76:79], v35 offset:30192
	ds_read_b32 v94, v36 offset:1920
	ds_read_b32 v95, v38 offset:1920
	ds_read_b128 v[68:71], v35 offset:12784
	ds_read_b128 v[72:75], v35 offset:21488
	ds_read_b128 v[80:83], v35 offset:38896
	v_pk_mul_f32 v[8:9], v[0:1], v[48:49] op_sel_hi:[1,0]
	v_pk_mul_f32 v[10:11], v[0:1], v[84:85] op_sel_hi:[1,0]
	v_pk_fma_f32 v[8:9], v[2:3], v[48:49], v[8:9] op_sel:[0,1,0] op_sel_hi:[1,1,1]
	v_pk_fma_f32 v[10:11], v[2:3], v[84:85], v[10:11] op_sel:[0,1,0] op_sel_hi:[1,1,1]
	v_pk_fma_f32 v[8:9], v[4:5], v[50:51], v[8:9] op_sel_hi:[1,0,1]
	v_pk_fma_f32 v[10:11], v[4:5], v[86:87], v[10:11] op_sel_hi:[1,0,1]
	v_pk_fma_f32 v[8:9], v[6:7], v[50:51], v[8:9] op_sel:[0,1,0] op_sel_hi:[1,1,1]
	v_pk_fma_f32 v[10:11], v[6:7], v[86:87], v[10:11] op_sel:[0,1,0] op_sel_hi:[1,1,1]
	v_readlane_b32 s10, v34, 14
	v_pk_mul_f32 v[16:17], v[92:93], v[60:61] op_sel_hi:[1,0]
	v_pk_mul_f32 v[18:19], v[92:93], v[60:61] op_sel:[0,1] op_sel_hi:[1,1]
	v_add_f32_dpp v8, v9, v8 quad_perm:[1,0,3,2] row_mask:0xf bank_mask:0xf bound_ctrl:1
	v_add_f32_dpp v10, v11, v10 quad_perm:[1,0,3,2] row_mask:0xf bank_mask:0xf bound_ctrl:1
	v_pk_mul_f32 v[20:21], v[92:93], v[62:63] op_sel_hi:[1,0]
	v_pk_mul_f32 v[22:23], v[92:93], v[62:63] op_sel:[0,1] op_sel_hi:[1,1]
	v_add_f32_dpp v8, v8, v8 quad_perm:[2,3,0,1] row_mask:0xf bank_mask:0xf bound_ctrl:1
	v_add_f32_dpp v10, v10, v10 quad_perm:[2,3,0,1] row_mask:0xf bank_mask:0xf bound_ctrl:1
	v_pk_fma_f32 v[0:1], v[0:1], v[52:53], v[16:17] op_sel_hi:[1,0,1]
	v_pk_fma_f32 v[2:3], v[2:3], v[52:53], v[18:19] op_sel:[0,1,0] op_sel_hi:[1,1,1]
	v_add_f32_dpp v8, v8, v8 row_ror:4 row_mask:0xf bank_mask:0xf bound_ctrl:1
	v_add_f32_dpp v10, v10, v10 row_ror:4 row_mask:0xf bank_mask:0xf bound_ctrl:1
	v_pk_fma_f32 v[4:5], v[4:5], v[54:55], v[20:21] op_sel_hi:[1,0,1]
	v_add_f32_dpp v8, v8, v8 row_ror:8 row_mask:0xf bank_mask:0xf bound_ctrl:1
	v_mul_f32_e32 v8, s10, v8
	v_add_f32_dpp v99, v10, v10 row_ror:8 row_mask:0xf bank_mask:0x2 bound_ctrl:1
	v_pk_fma_f32 v[6:7], v[6:7], v[54:55], v[22:23] op_sel:[0,1,0] op_sel_hi:[1,1,1]
	v_mov_b32_dpp v9, v8 quad_perm:[1,0,3,2] row_mask:0xf bank_mask:0xf
	v_pk_fma_f32 v[0:1], v[8:9], v[56:57], v[0:1] op_sel_hi:[1,0,1] neg_lo:[1,0,0] neg_hi:[1,0,0]
	v_pk_fma_f32 v[2:3], v[8:9], v[56:57], v[2:3] op_sel:[0,1,0] op_sel_hi:[1,1,1] neg_lo:[1,0,0] neg_hi:[1,0,0]
	v_pk_fma_f32 v[4:5], v[8:9], v[58:59], v[4:5] op_sel_hi:[1,0,1] neg_lo:[1,0,0] neg_hi:[1,0,0]
	v_pk_fma_f32 v[6:7], v[8:9], v[58:59], v[6:7] op_sel:[0,1,0] op_sel_hi:[1,1,1] neg_lo:[1,0,0] neg_hi:[1,0,0]
	s_waitcnt lgkmcnt(0)
	ds_read_b128 v[48:51], v35 offset:4352
	ds_read_b128 v[60:63], v35 offset:30464
	ds_read_b32 v92, v36 offset:2048
	ds_read_b32 v93, v38 offset:2048
	ds_read_b128 v[52:55], v35 offset:13056
	ds_read_b128 v[56:59], v35 offset:21760
	ds_read_b128 v[84:87], v35 offset:39168
	v_pk_mul_f32 v[8:9], v[0:1], v[64:65] op_sel_hi:[1,0]
	v_pk_mul_f32 v[10:11], v[0:1], v[88:89] op_sel_hi:[1,0]
	v_pk_fma_f32 v[8:9], v[2:3], v[64:65], v[8:9] op_sel:[0,1,0] op_sel_hi:[1,1,1]
	v_pk_fma_f32 v[10:11], v[2:3], v[88:89], v[10:11] op_sel:[0,1,0] op_sel_hi:[1,1,1]
	v_pk_fma_f32 v[8:9], v[4:5], v[66:67], v[8:9] op_sel_hi:[1,0,1]
	v_pk_fma_f32 v[10:11], v[4:5], v[90:91], v[10:11] op_sel_hi:[1,0,1]
	v_pk_fma_f32 v[8:9], v[6:7], v[66:67], v[8:9] op_sel:[0,1,0] op_sel_hi:[1,1,1]
	v_pk_fma_f32 v[10:11], v[6:7], v[90:91], v[10:11] op_sel:[0,1,0] op_sel_hi:[1,1,1]
	v_readlane_b32 s10, v34, 15
	v_pk_mul_f32 v[16:17], v[94:95], v[76:77] op_sel_hi:[1,0]
	v_pk_mul_f32 v[18:19], v[94:95], v[76:77] op_sel:[0,1] op_sel_hi:[1,1]
	v_add_f32_dpp v8, v9, v8 quad_perm:[1,0,3,2] row_mask:0xf bank_mask:0xf bound_ctrl:1
	v_add_f32_dpp v10, v11, v10 quad_perm:[1,0,3,2] row_mask:0xf bank_mask:0xf bound_ctrl:1
	v_pk_mul_f32 v[20:21], v[94:95], v[78:79] op_sel_hi:[1,0]
	v_pk_mul_f32 v[22:23], v[94:95], v[78:79] op_sel:[0,1] op_sel_hi:[1,1]
	v_add_f32_dpp v8, v8, v8 quad_perm:[2,3,0,1] row_mask:0xf bank_mask:0xf bound_ctrl:1
	v_add_f32_dpp v10, v10, v10 quad_perm:[2,3,0,1] row_mask:0xf bank_mask:0xf bound_ctrl:1
	v_pk_fma_f32 v[0:1], v[0:1], v[68:69], v[16:17] op_sel_hi:[1,0,1]
	v_pk_fma_f32 v[2:3], v[2:3], v[68:69], v[18:19] op_sel:[0,1,0] op_sel_hi:[1,1,1]
	v_add_f32_dpp v8, v8, v8 row_ror:4 row_mask:0xf bank_mask:0xf bound_ctrl:1
	v_add_f32_dpp v10, v10, v10 row_ror:4 row_mask:0xf bank_mask:0xf bound_ctrl:1
	v_pk_fma_f32 v[4:5], v[4:5], v[70:71], v[20:21] op_sel_hi:[1,0,1]
	v_add_f32_dpp v8, v8, v8 row_ror:8 row_mask:0xf bank_mask:0xf bound_ctrl:1
	v_mul_f32_e32 v8, s10, v8
	v_add_f32_dpp v99, v10, v10 row_ror:8 row_mask:0xf bank_mask:0x4 bound_ctrl:1
	v_pk_fma_f32 v[6:7], v[6:7], v[70:71], v[22:23] op_sel:[0,1,0] op_sel_hi:[1,1,1]
	v_mov_b32_dpp v9, v8 quad_perm:[1,0,3,2] row_mask:0xf bank_mask:0xf
	v_pk_fma_f32 v[0:1], v[8:9], v[72:73], v[0:1] op_sel_hi:[1,0,1] neg_lo:[1,0,0] neg_hi:[1,0,0]
	v_pk_fma_f32 v[2:3], v[8:9], v[72:73], v[2:3] op_sel:[0,1,0] op_sel_hi:[1,1,1] neg_lo:[1,0,0] neg_hi:[1,0,0]
	v_pk_fma_f32 v[4:5], v[8:9], v[74:75], v[4:5] op_sel_hi:[1,0,1] neg_lo:[1,0,0] neg_hi:[1,0,0]
	v_pk_fma_f32 v[6:7], v[8:9], v[74:75], v[6:7] op_sel:[0,1,0] op_sel_hi:[1,1,1] neg_lo:[1,0,0] neg_hi:[1,0,0]
	s_waitcnt lgkmcnt(0)
; #define VPKMUL(d, a, b) asm volatile("v_pk_mul_f32 %0, %1, %2" : "=v"(d) : "v"(a), "v"(b))
; __device__ __forceinline__ void scan_half(const Params& p, LAS unsigned char* lds, int pi, int rh, int pass) {
;     ...
;                 LOADREC(0, 0);
;                 float yp = 0.f, yk0 = 0.f, yk1 = 0.f, yk2 = 0.f, yk3 = 0.f;
;     ...
; #pragma unroll
;                 for (int s = 0; s < 32; ++s) {
;                     const int c = s & 1, pc = c ^ 1;
;                     const float si = __int_as_float(__builtin_amdgcn_readlane(__float_as_int(inv2), s));
;                     f32x2 px, py, t01, t23, t45, t67; float x;
;                     f32x2 vv2; vv2.x = Rv[c]; asm volatile("" : "+v"(vv2));
;                     if (s >= 1) {
;                         VPKMUL(px, P01, Rkk[c][0].xy); VPKMUL(py, P01, Rr[pc][0].xy); VPKFMA(px, P23, Rkk[c][0].zw, px); VPKFMA(py, P23, Rr[pc][0].zw, py);
;                         VPKFMA(px, P45, Rkk[c][1].xy, px); VPKFMA(py, P45, Rr[pc][1].xy, py); VPKFMA(px, P67, Rkk[c][1].zw, px); VPKFMA(py, P67, Rr[pc][1].zw, py);
;                         VADD(x, px.x, px.y); VADD(yp, py.x, py.y);
;                     } else {
;                         VPKMUL(px, P01, Rkk[c][0].xy); VPKFMA(px, P23, Rkk[c][0].zw, px); VPKFMA(px, P45, Rkk[c][1].xy, px); VPKFMA(px, P67, Rkk[c][1].zw, px);
;                         VADD(x, px.x, px.y);
;                     }
;                     asm volatile("" ::: "memory");
;                     if (s + 1 < 32) LOADREC((s + 1) & 1, s + 1);
;                     asm volatile("" ::: "memory");
;                     VPKMULBL(t01, vv2, Rkm[c][0].xy); VPKMULBL(t23, vv2, Rkm[c][0].zw);
;                     VDPP1(x); if (s >= 1) VDPP1(yp);
;                     VPKMULBL(t45, vv2, Rkm[c][1].xy); VPKMULBL(t67, vv2, Rkm[c][1].zw);
;                     VDPP2(x); if (s >= 1) VDPP2(yp);
;                     VPKFMA(P01, P01, Rw[c][0].xy, t01); VPKFMA(P23, P23, Rw[c][0].zw, t23);
;                     VDPP3(x); if (s >= 1) VDPP3(yp);
;                     VPKFMA(P45, P45, Rw[c][1].xy, t45); VPKFMA(P67, P67, Rw[c][1].zw, t67);
;                     if (s >= 1) { if (s - 1 < 8) YSHIFT(yk0); else if (s - 1 < 16) YSHIFT(yk1); else if (s - 1 < 24) YSHIFT(yk2); else YSHIFT(yk3); }
;                     x = x * si;
;                     f32x2 x2; x2.x = x; asm volatile("" : "+v"(x2));
	ds_read_b128 v[64:67], v35 offset:4624
	ds_read_b128 v[76:79], v35 offset:30736
	ds_read_b32 v94, v36 offset:2176
	ds_read_b32 v95, v38 offset:2176
	ds_read_b128 v[68:71], v35 offset:13328
	ds_read_b128 v[72:75], v35 offset:22032
	ds_read_b128 v[88:91], v35 offset:39440
	v_pk_mul_f32 v[8:9], v[0:1], v[48:49] op_sel_hi:[1,0]
	v_pk_mul_f32 v[10:11], v[0:1], v[80:81] op_sel_hi:[1,0]
	v_pk_fma_f32 v[8:9], v[2:3], v[48:49], v[8:9] op_sel:[0,1,0] op_sel_hi:[1,1,1]
	v_pk_fma_f32 v[10:11], v[2:3], v[80:81], v[10:11] op_sel:[0,1,0] op_sel_hi:[1,1,1]
	v_pk_fma_f32 v[8:9], v[4:5], v[50:51], v[8:9] op_sel_hi:[1,0,1]
	v_pk_fma_f32 v[10:11], v[4:5], v[82:83], v[10:11] op_sel_hi:[1,0,1]
	v_pk_fma_f32 v[8:9], v[6:7], v[50:51], v[8:9] op_sel:[0,1,0] op_sel_hi:[1,1,1]
	v_pk_fma_f32 v[10:11], v[6:7], v[82:83], v[10:11] op_sel:[0,1,0] op_sel_hi:[1,1,1]
	v_readlane_b32 s10, v34, 16
	v_pk_mul_f32 v[16:17], v[92:93], v[60:61] op_sel_hi:[1,0]
	v_pk_mul_f32 v[18:19], v[92:93], v[60:61] op_sel:[0,1] op_sel_hi:[1,1]
	v_add_f32_dpp v8, v9, v8 quad_perm:[1,0,3,2] row_mask:0xf bank_mask:0xf bound_ctrl:1
	v_add_f32_dpp v10, v11, v10 quad_perm:[1,0,3,2] row_mask:0xf bank_mask:0xf bound_ctrl:1
	v_pk_mul_f32 v[20:21], v[92:93], v[62:63] op_sel_hi:[1,0]
	v_pk_mul_f32 v[22:23], v[92:93], v[62:63] op_sel:[0,1] op_sel_hi:[1,1]
	v_add_f32_dpp v8, v8, v8 quad_perm:[2,3,0,1] row_mask:0xf bank_mask:0xf bound_ctrl:1
	v_add_f32_dpp v10, v10, v10 quad_perm:[2,3,0,1] row_mask:0xf bank_mask:0xf bound_ctrl:1
	v_pk_fma_f32 v[0:1], v[0:1], v[52:53], v[16:17] op_sel_hi:[1,0,1]
	v_pk_fma_f32 v[2:3], v[2:3], v[52:53], v[18:19] op_sel:[0,1,0] op_sel_hi:[1,1,1]
	v_add_f32_dpp v8, v8, v8 row_ror:4 row_mask:0xf bank_mask:0xf bound_ctrl:1
	v_add_f32_dpp v10, v10, v10 row_ror:4 row_mask:0xf bank_mask:0xf bound_ctrl:1
	v_pk_fma_f32 v[4:5], v[4:5], v[54:55], v[20:21] op_sel_hi:[1,0,1]
	v_add_f32_dpp v8, v8, v8 row_ror:8 row_mask:0xf bank_mask:0xf bound_ctrl:1
	v_mul_f32_e32 v8, s10, v8
	v_add_f32_dpp v99, v10, v10 row_ror:8 row_mask:0xf bank_mask:0x8 bound_ctrl:1
	v_pk_fma_f32 v[6:7], v[6:7], v[54:55], v[22:23] op_sel:[0,1,0] op_sel_hi:[1,1,1]
	v_mov_b32_dpp v9, v8 quad_perm:[1,0,3,2] row_mask:0xf bank_mask:0xf
	v_pk_fma_f32 v[0:1], v[8:9], v[56:57], v[0:1] op_sel_hi:[1,0,1] neg_lo:[1,0,0] neg_hi:[1,0,0]
	v_pk_fma_f32 v[2:3], v[8:9], v[56:57], v[2:3] op_sel:[0,1,0] op_sel_hi:[1,1,1] neg_lo:[1,0,0] neg_hi:[1,0,0]
	v_pk_fma_f32 v[4:5], v[8:9], v[58:59], v[4:5] op_sel_hi:[1,0,1] neg_lo:[1,0,0] neg_hi:[1,0,0]
	v_pk_fma_f32 v[6:7], v[8:9], v[58:59], v[6:7] op_sel:[0,1,0] op_sel_hi:[1,1,1] neg_lo:[1,0,0] neg_hi:[1,0,0]
	s_waitcnt lgkmcnt(0)
	ds_read_b128 v[48:51], v35 offset:4896
	ds_read_b128 v[60:63], v35 offset:31008
	ds_read_b32 v92, v36 offset:2304
	ds_read_b32 v93, v38 offset:2304
	ds_read_b128 v[52:55], v35 offset:13600
	ds_read_b128 v[56:59], v35 offset:22304
	ds_read_b128 v[80:83], v35 offset:39712
	v_pk_mul_f32 v[8:9], v[0:1], v[64:65] op_sel_hi:[1,0]
	v_pk_mul_f32 v[10:11], v[0:1], v[84:85] op_sel_hi:[1,0]
	v_pk_fma_f32 v[8:9], v[2:3], v[64:65], v[8:9] op_sel:[0,1,0] op_sel_hi:[1,1,1]
	v_pk_fma_f32 v[10:11], v[2:3], v[84:85], v[10:11] op_sel:[0,1,0] op_sel_hi:[1,1,1]
	v_pk_fma_f32 v[8:9], v[4:5], v[66:67], v[8:9] op_sel_hi:[1,0,1]
	v_pk_fma_f32 v[10:11], v[4:5], v[86:87], v[10:11] op_sel_hi:[1,0,1]
	v_pk_fma_f32 v[8:9], v[6:7], v[66:67], v[8:9] op_sel:[0,1,0] op_sel_hi:[1,1,1]
	v_pk_fma_f32 v[10:11], v[6:7], v[86:87], v[10:11] op_sel:[0,1,0] op_sel_hi:[1,1,1]
	v_readlane_b32 s10, v34, 17
	v_pk_mul_f32 v[16:17], v[94:95], v[76:77] op_sel_hi:[1,0]
	v_pk_mul_f32 v[18:19], v[94:95], v[76:77] op_sel:[0,1] op_sel_hi:[1,1]
	v_add_f32_dpp v8, v9, v8 quad_perm:[1,0,3,2] row_mask:0xf bank_mask:0xf bound_ctrl:1
	v_add_f32_dpp v10, v11, v10 quad_perm:[1,0,3,2] row_mask:0xf bank_mask:0xf bound_ctrl:1
	v_pk_mul_f32 v[20:21], v[94:95], v[78:79] op_sel_hi:[1,0]
	v_pk_mul_f32 v[22:23], v[94:95], v[78:79] op_sel:[0,1] op_sel_hi:[1,1]
	v_add_f32_dpp v8, v8, v8 quad_perm:[2,3,0,1] row_mask:0xf bank_mask:0xf bound_ctrl:1
	v_add_f32_dpp v10, v10, v10 quad_perm:[2,3,0,1] row_mask:0xf bank_mask:0xf bound_ctrl:1
	v_pk_fma_f32 v[0:1], v[0:1], v[68:69], v[16:17] op_sel_hi:[1,0,1]
	v_pk_fma_f32 v[2:3], v[2:3], v[68:69], v[18:19] op_sel:[0,1,0] op_sel_hi:[1,1,1]
	v_add_f32_dpp v8, v8, v8 row_ror:4 row_mask:0xf bank_mask:0xf bound_ctrl:1
	v_add_f32_dpp v10, v10, v10 row_ror:4 row_mask:0xf bank_mask:0xf bound_ctrl:1
	v_pk_fma_f32 v[4:5], v[4:5], v[70:71], v[20:21] op_sel_hi:[1,0,1]
	v_add_f32_dpp v8, v8, v8 row_ror:8 row_mask:0xf bank_mask:0xf bound_ctrl:1
	v_mul_f32_e32 v8, s10, v8
	v_add_f32_dpp v100, v10, v10 row_ror:8 row_mask:0xf bank_mask:0x1 bound_ctrl:1
	v_pk_fma_f32 v[6:7], v[6:7], v[70:71], v[22:23] op_sel:[0,1,0] op_sel_hi:[1,1,1]
	v_mov_b32_dpp v9, v8 quad_perm:[1,0,3,2] row_mask:0xf bank_mask:0xf
	v_pk_fma_f32 v[0:1], v[8:9], v[72:73], v[0:1] op_sel_hi:[1,0,1] neg_lo:[1,0,0] neg_hi:[1,0,0]
	v_pk_fma_f32 v[2:3], v[8:9], v[72:73], v[2:3] op_sel:[0,1,0] op_sel_hi:[1,1,1] neg_lo:[1,0,0] neg_hi:[1,0,0]
	v_pk_fma_f32 v[4:5], v[8:9], v[74:75], v[4:5] op_sel_hi:[1,0,1] neg_lo:[1,0,0] neg_hi:[1,0,0]
	v_pk_fma_f32 v[6:7], v[8:9], v[74:75], v[6:7] op_sel:[0,1,0] op_sel_hi:[1,1,1] neg_lo:[1,0,0] neg_hi:[1,0,0]
	s_waitcnt lgkmcnt(0)
; #define VPKMUL(d, a, b) asm volatile("v_pk_mul_f32 %0, %1, %2" : "=v"(d) : "v"(a), "v"(b))
; __device__ __forceinline__ void scan_half(const Params& p, LAS unsigned char* lds, int pi, int rh, int pass) {
;     ...
;                 LOADREC(0, 0);
;                 float yp = 0.f, yk0 = 0.f, yk1 = 0.f, yk2 = 0.f, yk3 = 0.f;
;     ...
; #pragma unroll
;                 for (int s = 0; s < 32; ++s) {
;                     const int c = s & 1, pc = c ^ 1;
;                     const float si = __int_as_float(__builtin_amdgcn_readlane(__float_as_int(inv2), s));
;                     f32x2 px, py, t01, t23, t45, t67; float x;
;                     f32x2 vv2; vv2.x = Rv[c]; asm volatile("" : "+v"(vv2));
;                     if (s >= 1) {
;                         VPKMUL(px, P01, Rkk[c][0].xy); VPKMUL(py, P01, Rr[pc][0].xy); VPKFMA(px, P23, Rkk[c][0].zw, px); VPKFMA(py, P23, Rr[pc][0].zw, py);
;                         VPKFMA(px, P45, Rkk[c][1].xy, px); VPKFMA(py, P45, Rr[pc][1].xy, py); VPKFMA(px, P67, Rkk[c][1].zw, px); VPKFMA(py, P67, Rr[pc][1].zw, py);
;                         VADD(x, px.x, px.y); VADD(yp, py.x, py.y);
;                     } else {
;                         VPKMUL(px, P01, Rkk[c][0].xy); VPKFMA(px, P23, Rkk[c][0].zw, px); VPKFMA(px, P45, Rkk[c][1].xy, px); VPKFMA(px, P67, Rkk[c][1].zw, px);
;                         VADD(x, px.x, px.y);
;                     }
;                     asm volatile("" ::: "memory");
;                     if (s + 1 < 32) LOADREC((s + 1) & 1, s + 1);
;                     asm volatile("" ::: "memory");
;                     VPKMULBL(t01, vv2, Rkm[c][0].xy); VPKMULBL(t23, vv2, Rkm[c][0].zw);
;                     VDPP1(x); if (s >= 1) VDPP1(yp);
;                     VPKMULBL(t45, vv2, Rkm[c][1].xy); VPKMULBL(t67, vv2, Rkm[c][1].zw);
;                     VDPP2(x); if (s >= 1) VDPP2(yp);
;                     VPKFMA(P01, P01, Rw[c][0].xy, t01); VPKFMA(P23, P23, Rw[c][0].zw, t23);
;                     VDPP3(x); if (s >= 1) VDPP3(yp);
;                     VPKFMA(P45, P45, Rw[c][1].xy, t45); VPKFMA(P67, P67, Rw[c][1].zw, t67);
;                     if (s >= 1) { if (s - 1 < 8) YSHIFT(yk0); else if (s - 1 < 16) YSHIFT(yk1); else if (s - 1 < 24) YSHIFT(yk2); else YSHIFT(yk3); }
;                     x = x * si;
;                     f32x2 x2; x2.x = x; asm volatile("" : "+v"(x2));
	ds_read_b128 v[64:67], v35 offset:5168
	ds_read_b128 v[76:79], v35 offset:31280
	ds_read_b32 v94, v36 offset:2432
	ds_read_b32 v95, v38 offset:2432
	ds_read_b128 v[68:71], v35 offset:13872
	ds_read_b128 v[72:75], v35 offset:22576
	ds_read_b128 v[84:87], v35 offset:39984
	v_pk_mul_f32 v[8:9], v[0:1], v[48:49] op_sel_hi:[1,0]
	v_pk_mul_f32 v[10:11], v[0:1], v[88:89] op_sel_hi:[1,0]
	v_pk_fma_f32 v[8:9], v[2:3], v[48:49], v[8:9] op_sel:[0,1,0] op_sel_hi:[1,1,1]
	v_pk_fma_f32 v[10:11], v[2:3], v[88:89], v[10:11] op_sel:[0,1,0] op_sel_hi:[1,1,1]
	v_pk_fma_f32 v[8:9], v[4:5], v[50:51], v[8:9] op_sel_hi:[1,0,1]
	v_pk_fma_f32 v[10:11], v[4:5], v[90:91], v[10:11] op_sel_hi:[1,0,1]
	v_pk_fma_f32 v[8:9], v[6:7], v[50:51], v[8:9] op_sel:[0,1,0] op_sel_hi:[1,1,1]
	v_pk_fma_f32 v[10:11], v[6:7], v[90:91], v[10:11] op_sel:[0,1,0] op_sel_hi:[1,1,1]
	v_readlane_b32 s10, v34, 18
	v_pk_mul_f32 v[16:17], v[92:93], v[60:61] op_sel_hi:[1,0]
	v_pk_mul_f32 v[18:19], v[92:93], v[60:61] op_sel:[0,1] op_sel_hi:[1,1]
	v_add_f32_dpp v8, v9, v8 quad_perm:[1,0,3,2] row_mask:0xf bank_mask:0xf bound_ctrl:1
	v_add_f32_dpp v10, v11, v10 quad_perm:[1,0,3,2] row_mask:0xf bank_mask:0xf bound_ctrl:1
	v_pk_mul_f32 v[20:21], v[92:93], v[62:63] op_sel_hi:[1,0]
	v_pk_mul_f32 v[22:23], v[92:93], v[62:63] op_sel:[0,1] op_sel_hi:[1,1]
	v_add_f32_dpp v8, v8, v8 quad_perm:[2,3,0,1] row_mask:0xf bank_mask:0xf bound_ctrl:1
	v_add_f32_dpp v10, v10, v10 quad_perm:[2,3,0,1] row_mask:0xf bank_mask:0xf bound_ctrl:1
	v_pk_fma_f32 v[0:1], v[0:1], v[52:53], v[16:17] op_sel_hi:[1,0,1]
	v_pk_fma_f32 v[2:3], v[2:3], v[52:53], v[18:19] op_sel:[0,1,0] op_sel_hi:[1,1,1]
	v_add_f32_dpp v8, v8, v8 row_ror:4 row_mask:0xf bank_mask:0xf bound_ctrl:1
	v_add_f32_dpp v10, v10, v10 row_ror:4 row_mask:0xf bank_mask:0xf bound_ctrl:1
	v_pk_fma_f32 v[4:5], v[4:5], v[54:55], v[20:21] op_sel_hi:[1,0,1]
	v_add_f32_dpp v8, v8, v8 row_ror:8 row_mask:0xf bank_mask:0xf bound_ctrl:1
	v_mul_f32_e32 v8, s10, v8
	v_add_f32_dpp v100, v10, v10 row_ror:8 row_mask:0xf bank_mask:0x2 bound_ctrl:1
	v_pk_fma_f32 v[6:7], v[6:7], v[54:55], v[22:23] op_sel:[0,1,0] op_sel_hi:[1,1,1]
	v_mov_b32_dpp v9, v8 quad_perm:[1,0,3,2] row_mask:0xf bank_mask:0xf
	v_pk_fma_f32 v[0:1], v[8:9], v[56:57], v[0:1] op_sel_hi:[1,0,1] neg_lo:[1,0,0] neg_hi:[1,0,0]
	v_pk_fma_f32 v[2:3], v[8:9], v[56:57], v[2:3] op_sel:[0,1,0] op_sel_hi:[1,1,1] neg_lo:[1,0,0] neg_hi:[1,0,0]
	v_pk_fma_f32 v[4:5], v[8:9], v[58:59], v[4:5] op_sel_hi:[1,0,1] neg_lo:[1,0,0] neg_hi:[1,0,0]
	v_pk_fma_f32 v[6:7], v[8:9], v[58:59], v[6:7] op_sel:[0,1,0] op_sel_hi:[1,1,1] neg_lo:[1,0,0] neg_hi:[1,0,0]
	s_waitcnt lgkmcnt(0)
	ds_read_b128 v[48:51], v35 offset:5440
	ds_read_b128 v[60:63], v35 offset:31552
	ds_read_b32 v92, v36 offset:2560
	ds_read_b32 v93, v38 offset:2560
	ds_read_b128 v[52:55], v35 offset:14144
	ds_read_b128 v[56:59], v35 offset:22848
	ds_read_b128 v[88:91], v35 offset:40256
	v_pk_mul_f32 v[8:9], v[0:1], v[64:65] op_sel_hi:[1,0]
	v_pk_mul_f32 v[10:11], v[0:1], v[80:81] op_sel_hi:[1,0]
	v_pk_fma_f32 v[8:9], v[2:3], v[64:65], v[8:9] op_sel:[0,1,0] op_sel_hi:[1,1,1]
	v_pk_fma_f32 v[10:11], v[2:3], v[80:81], v[10:11] op_sel:[0,1,0] op_sel_hi:[1,1,1]
	v_pk_fma_f32 v[8:9], v[4:5], v[66:67], v[8:9] op_sel_hi:[1,0,1]
	v_pk_fma_f32 v[10:11], v[4:5], v[82:83], v[10:11] op_sel_hi:[1,0,1]
	v_pk_fma_f32 v[8:9], v[6:7], v[66:67], v[8:9] op_sel:[0,1,0] op_sel_hi:[1,1,1]
	v_pk_fma_f32 v[10:11], v[6:7], v[82:83], v[10:11] op_sel:[0,1,0] op_sel_hi:[1,1,1]
	v_readlane_b32 s10, v34, 19
	v_pk_mul_f32 v[16:17], v[94:95], v[76:77] op_sel_hi:[1,0]
	v_pk_mul_f32 v[18:19], v[94:95], v[76:77] op_sel:[0,1] op_sel_hi:[1,1]
	v_add_f32_dpp v8, v9, v8 quad_perm:[1,0,3,2] row_mask:0xf bank_mask:0xf bound_ctrl:1
	v_add_f32_dpp v10, v11, v10 quad_perm:[1,0,3,2] row_mask:0xf bank_mask:0xf bound_ctrl:1
	v_pk_mul_f32 v[20:21], v[94:95], v[78:79] op_sel_hi:[1,0]
	v_pk_mul_f32 v[22:23], v[94:95], v[78:79] op_sel:[0,1] op_sel_hi:[1,1]
	v_add_f32_dpp v8, v8, v8 quad_perm:[2,3,0,1] row_mask:0xf bank_mask:0xf bound_ctrl:1
	v_add_f32_dpp v10, v10, v10 quad_perm:[2,3,0,1] row_mask:0xf bank_mask:0xf bound_ctrl:1
	v_pk_fma_f32 v[0:1], v[0:1], v[68:69], v[16:17] op_sel_hi:[1,0,1]
	v_pk_fma_f32 v[2:3], v[2:3], v[68:69], v[18:19] op_sel:[0,1,0] op_sel_hi:[1,1,1]
	v_add_f32_dpp v8, v8, v8 row_ror:4 row_mask:0xf bank_mask:0xf bound_ctrl:1
	v_add_f32_dpp v10, v10, v10 row_ror:4 row_mask:0xf bank_mask:0xf bound_ctrl:1
	v_pk_fma_f32 v[4:5], v[4:5], v[70:71], v[20:21] op_sel_hi:[1,0,1]
	v_add_f32_dpp v8, v8, v8 row_ror:8 row_mask:0xf bank_mask:0xf bound_ctrl:1
	v_mul_f32_e32 v8, s10, v8
	v_add_f32_dpp v100, v10, v10 row_ror:8 row_mask:0xf bank_mask:0x4 bound_ctrl:1
	v_pk_fma_f32 v[6:7], v[6:7], v[70:71], v[22:23] op_sel:[0,1,0] op_sel_hi:[1,1,1]
	v_mov_b32_dpp v9, v8 quad_perm:[1,0,3,2] row_mask:0xf bank_mask:0xf
	v_pk_fma_f32 v[0:1], v[8:9], v[72:73], v[0:1] op_sel_hi:[1,0,1] neg_lo:[1,0,0] neg_hi:[1,0,0]
	v_pk_fma_f32 v[2:3], v[8:9], v[72:73], v[2:3] op_sel:[0,1,0] op_sel_hi:[1,1,1] neg_lo:[1,0,0] neg_hi:[1,0,0]
	v_pk_fma_f32 v[4:5], v[8:9], v[74:75], v[4:5] op_sel_hi:[1,0,1] neg_lo:[1,0,0] neg_hi:[1,0,0]
	v_pk_fma_f32 v[6:7], v[8:9], v[74:75], v[6:7] op_sel:[0,1,0] op_sel_hi:[1,1,1] neg_lo:[1,0,0] neg_hi:[1,0,0]
	s_waitcnt lgkmcnt(0)
; #define VPKMUL(d, a, b) asm volatile("v_pk_mul_f32 %0, %1, %2" : "=v"(d) : "v"(a), "v"(b))
; __device__ __forceinline__ void scan_half(const Params& p, LAS unsigned char* lds, int pi, int rh, int pass) {
;     ...
;                 LOADREC(0, 0);
;                 float yp = 0.f, yk0 = 0.f, yk1 = 0.f, yk2 = 0.f, yk3 = 0.f;
;     ...
; #pragma unroll
;                 for (int s = 0; s < 32; ++s) {
;                     const int c = s & 1, pc = c ^ 1;
;                     const float si = __int_as_float(__builtin_amdgcn_readlane(__float_as_int(inv2), s));
;                     f32x2 px, py, t01, t23, t45, t67; float x;
;                     f32x2 vv2; vv2.x = Rv[c]; asm volatile("" : "+v"(vv2));
;                     if (s >= 1) {
;                         VPKMUL(px, P01, Rkk[c][0].xy); VPKMUL(py, P01, Rr[pc][0].xy); VPKFMA(px, P23, Rkk[c][0].zw, px); VPKFMA(py, P23, Rr[pc][0].zw, py);
;                         VPKFMA(px, P45, Rkk[c][1].xy, px); VPKFMA(py, P45, Rr[pc][1].xy, py); VPKFMA(px, P67, Rkk[c][1].zw, px); VPKFMA(py, P67, Rr[pc][1].zw, py);
;                         VADD(x, px.x, px.y); VADD(yp, py.x, py.y);
;                     } else {
;                         VPKMUL(px, P01, Rkk[c][0].xy); VPKFMA(px, P23, Rkk[c][0].zw, px); VPKFMA(px, P45, Rkk[c][1].xy, px); VPKFMA(px, P67, Rkk[c][1].zw, px);
;                         VADD(x, px.x, px.y);
;                     }
;                     asm volatile("" ::: "memory");
;                     if (s + 1 < 32) LOADREC((s + 1) & 1, s + 1);
;                     asm volatile("" ::: "memory");
;                     VPKMULBL(t01, vv2, Rkm[c][0].xy); VPKMULBL(t23, vv2, Rkm[c][0].zw);
;                     VDPP1(x); if (s >= 1) VDPP1(yp);
;                     VPKMULBL(t45, vv2, Rkm[c][1].xy); VPKMULBL(t67, vv2, Rkm[c][1].zw);
;                     VDPP2(x); if (s >= 1) VDPP2(yp);
;                     VPKFMA(P01, P01, Rw[c][0].xy, t01); VPKFMA(P23, P23, Rw[c][0].zw, t23);
;                     VDPP3(x); if (s >= 1) VDPP3(yp);
;                     VPKFMA(P45, P45, Rw[c][1].xy, t45); VPKFMA(P67, P67, Rw[c][1].zw, t67);
;                     if (s >= 1) { if (s - 1 < 8) YSHIFT(yk0); else if (s - 1 < 16) YSHIFT(yk1); else if (s - 1 < 24) YSHIFT(yk2); else YSHIFT(yk3); }
;                     x = x * si;
;                     f32x2 x2; x2.x = x; asm volatile("" : "+v"(x2));
	ds_read_b128 v[64:67], v35 offset:5712
	ds_read_b128 v[76:79], v35 offset:31824
	ds_read_b32 v94, v36 offset:2688
	ds_read_b32 v95, v38 offset:2688
	ds_read_b128 v[68:71], v35 offset:14416
	ds_read_b128 v[72:75], v35 offset:23120
	ds_read_b128 v[80:83], v35 offset:40528
	v_pk_mul_f32 v[8:9], v[0:1], v[48:49] op_sel_hi:[1,0]
	v_pk_mul_f32 v[10:11], v[0:1], v[84:85] op_sel_hi:[1,0]
	v_pk_fma_f32 v[8:9], v[2:3], v[48:49], v[8:9] op_sel:[0,1,0] op_sel_hi:[1,1,1]
	v_pk_fma_f32 v[10:11], v[2:3], v[84:85], v[10:11] op_sel:[0,1,0] op_sel_hi:[1,1,1]
	v_pk_fma_f32 v[8:9], v[4:5], v[50:51], v[8:9] op_sel_hi:[1,0,1]
	v_pk_fma_f32 v[10:11], v[4:5], v[86:87], v[10:11] op_sel_hi:[1,0,1]
	v_pk_fma_f32 v[8:9], v[6:7], v[50:51], v[8:9] op_sel:[0,1,0] op_sel_hi:[1,1,1]
	v_pk_fma_f32 v[10:11], v[6:7], v[86:87], v[10:11] op_sel:[0,1,0] op_sel_hi:[1,1,1]
	v_readlane_b32 s10, v34, 20
	v_pk_mul_f32 v[16:17], v[92:93], v[60:61] op_sel_hi:[1,0]
	v_pk_mul_f32 v[18:19], v[92:93], v[60:61] op_sel:[0,1] op_sel_hi:[1,1]
	v_add_f32_dpp v8, v9, v8 quad_perm:[1,0,3,2] row_mask:0xf bank_mask:0xf bound_ctrl:1
	v_add_f32_dpp v10, v11, v10 quad_perm:[1,0,3,2] row_mask:0xf bank_mask:0xf bound_ctrl:1
	v_pk_mul_f32 v[20:21], v[92:93], v[62:63] op_sel_hi:[1,0]
	v_pk_mul_f32 v[22:23], v[92:93], v[62:63] op_sel:[0,1] op_sel_hi:[1,1]
	v_add_f32_dpp v8, v8, v8 quad_perm:[2,3,0,1] row_mask:0xf bank_mask:0xf bound_ctrl:1
	v_add_f32_dpp v10, v10, v10 quad_perm:[2,3,0,1] row_mask:0xf bank_mask:0xf bound_ctrl:1
	v_pk_fma_f32 v[0:1], v[0:1], v[52:53], v[16:17] op_sel_hi:[1,0,1]
	v_pk_fma_f32 v[2:3], v[2:3], v[52:53], v[18:19] op_sel:[0,1,0] op_sel_hi:[1,1,1]
	v_add_f32_dpp v8, v8, v8 row_ror:4 row_mask:0xf bank_mask:0xf bound_ctrl:1
	v_add_f32_dpp v10, v10, v10 row_ror:4 row_mask:0xf bank_mask:0xf bound_ctrl:1
	v_pk_fma_f32 v[4:5], v[4:5], v[54:55], v[20:21] op_sel_hi:[1,0,1]
	v_add_f32_dpp v8, v8, v8 row_ror:8 row_mask:0xf bank_mask:0xf bound_ctrl:1
	v_mul_f32_e32 v8, s10, v8
	v_add_f32_dpp v100, v10, v10 row_ror:8 row_mask:0xf bank_mask:0x8 bound_ctrl:1
	v_pk_fma_f32 v[6:7], v[6:7], v[54:55], v[22:23] op_sel:[0,1,0] op_sel_hi:[1,1,1]
	v_mov_b32_dpp v9, v8 quad_perm:[1,0,3,2] row_mask:0xf bank_mask:0xf
	v_pk_fma_f32 v[0:1], v[8:9], v[56:57], v[0:1] op_sel_hi:[1,0,1] neg_lo:[1,0,0] neg_hi:[1,0,0]
	v_pk_fma_f32 v[2:3], v[8:9], v[56:57], v[2:3] op_sel:[0,1,0] op_sel_hi:[1,1,1] neg_lo:[1,0,0] neg_hi:[1,0,0]
	v_pk_fma_f32 v[4:5], v[8:9], v[58:59], v[4:5] op_sel_hi:[1,0,1] neg_lo:[1,0,0] neg_hi:[1,0,0]
	v_pk_fma_f32 v[6:7], v[8:9], v[58:59], v[6:7] op_sel:[0,1,0] op_sel_hi:[1,1,1] neg_lo:[1,0,0] neg_hi:[1,0,0]
	s_waitcnt lgkmcnt(0)
	ds_read_b128 v[48:51], v35 offset:5984
	ds_read_b128 v[60:63], v35 offset:32096
	ds_read_b32 v92, v36 offset:2816
	ds_read_b32 v93, v38 offset:2816
	ds_read_b128 v[52:55], v35 offset:14688
	ds_read_b128 v[56:59], v35 offset:23392
	ds_read_b128 v[84:87], v35 offset:40800
	v_pk_mul_f32 v[8:9], v[0:1], v[64:65] op_sel_hi:[1,0]
	v_pk_mul_f32 v[10:11], v[0:1], v[88:89] op_sel_hi:[1,0]
	v_pk_fma_f32 v[8:9], v[2:3], v[64:65], v[8:9] op_sel:[0,1,0] op_sel_hi:[1,1,1]
	v_pk_fma_f32 v[10:11], v[2:3], v[88:89], v[10:11] op_sel:[0,1,0] op_sel_hi:[1,1,1]
	v_pk_fma_f32 v[8:9], v[4:5], v[66:67], v[8:9] op_sel_hi:[1,0,1]
	v_pk_fma_f32 v[10:11], v[4:5], v[90:91], v[10:11] op_sel_hi:[1,0,1]
	v_pk_fma_f32 v[8:9], v[6:7], v[66:67], v[8:9] op_sel:[0,1,0] op_sel_hi:[1,1,1]
	v_pk_fma_f32 v[10:11], v[6:7], v[90:91], v[10:11] op_sel:[0,1,0] op_sel_hi:[1,1,1]
	v_readlane_b32 s10, v34, 21
	v_pk_mul_f32 v[16:17], v[94:95], v[76:77] op_sel_hi:[1,0]
	v_pk_mul_f32 v[18:19], v[94:95], v[76:77] op_sel:[0,1] op_sel_hi:[1,1]
	v_add_f32_dpp v8, v9, v8 quad_perm:[1,0,3,2] row_mask:0xf bank_mask:0xf bound_ctrl:1
	v_add_f32_dpp v10, v11, v10 quad_perm:[1,0,3,2] row_mask:0xf bank_mask:0xf bound_ctrl:1
	v_pk_mul_f32 v[20:21], v[94:95], v[78:79] op_sel_hi:[1,0]
	v_pk_mul_f32 v[22:23], v[94:95], v[78:79] op_sel:[0,1] op_sel_hi:[1,1]
	v_add_f32_dpp v8, v8, v8 quad_perm:[2,3,0,1] row_mask:0xf bank_mask:0xf bound_ctrl:1
	v_add_f32_dpp v10, v10, v10 quad_perm:[2,3,0,1] row_mask:0xf bank_mask:0xf bound_ctrl:1
	v_pk_fma_f32 v[0:1], v[0:1], v[68:69], v[16:17] op_sel_hi:[1,0,1]
	v_pk_fma_f32 v[2:3], v[2:3], v[68:69], v[18:19] op_sel:[0,1,0] op_sel_hi:[1,1,1]
	v_add_f32_dpp v8, v8, v8 row_ror:4 row_mask:0xf bank_mask:0xf bound_ctrl:1
	v_add_f32_dpp v10, v10, v10 row_ror:4 row_mask:0xf bank_mask:0xf bound_ctrl:1
	v_pk_fma_f32 v[4:5], v[4:5], v[70:71], v[20:21] op_sel_hi:[1,0,1]
	v_add_f32_dpp v8, v8, v8 row_ror:8 row_mask:0xf bank_mask:0xf bound_ctrl:1
	v_mul_f32_e32 v8, s10, v8
	v_add_f32_dpp v101, v10, v10 row_ror:8 row_mask:0xf bank_mask:0x1 bound_ctrl:1
	v_pk_fma_f32 v[6:7], v[6:7], v[70:71], v[22:23] op_sel:[0,1,0] op_sel_hi:[1,1,1]
	v_mov_b32_dpp v9, v8 quad_perm:[1,0,3,2] row_mask:0xf bank_mask:0xf
	v_pk_fma_f32 v[0:1], v[8:9], v[72:73], v[0:1] op_sel_hi:[1,0,1] neg_lo:[1,0,0] neg_hi:[1,0,0]
	v_pk_fma_f32 v[2:3], v[8:9], v[72:73], v[2:3] op_sel:[0,1,0] op_sel_hi:[1,1,1] neg_lo:[1,0,0] neg_hi:[1,0,0]
	v_pk_fma_f32 v[4:5], v[8:9], v[74:75], v[4:5] op_sel_hi:[1,0,1] neg_lo:[1,0,0] neg_hi:[1,0,0]
	v_pk_fma_f32 v[6:7], v[8:9], v[74:75], v[6:7] op_sel:[0,1,0] op_sel_hi:[1,1,1] neg_lo:[1,0,0] neg_hi:[1,0,0]
	s_waitcnt lgkmcnt(0)
; #define VPKMUL(d, a, b) asm volatile("v_pk_mul_f32 %0, %1, %2" : "=v"(d) : "v"(a), "v"(b))
; __device__ __forceinline__ void scan_half(const Params& p, LAS unsigned char* lds, int pi, int rh, int pass) {
;     ...
;                 LOADREC(0, 0);
;                 float yp = 0.f, yk0 = 0.f, yk1 = 0.f, yk2 = 0.f, yk3 = 0.f;
;     ...
; #pragma unroll
;                 for (int s = 0; s < 32; ++s) {
;                     const int c = s & 1, pc = c ^ 1;
;                     const float si = __int_as_float(__builtin_amdgcn_readlane(__float_as_int(inv2), s));
;                     f32x2 px, py, t01, t23, t45, t67; float x;
;                     f32x2 vv2; vv2.x = Rv[c]; asm volatile("" : "+v"(vv2));
;                     if (s >= 1) {
;                         VPKMUL(px, P01, Rkk[c][0].xy); VPKMUL(py, P01, Rr[pc][0].xy); VPKFMA(px, P23, Rkk[c][0].zw, px); VPKFMA(py, P23, Rr[pc][0].zw, py);
;                         VPKFMA(px, P45, Rkk[c][1].xy, px); VPKFMA(py, P45, Rr[pc][1].xy, py); VPKFMA(px, P67, Rkk[c][1].zw, px); VPKFMA(py, P67, Rr[pc][1].zw, py);
;                         VADD(x, px.x, px.y); VADD(yp, py.x, py.y);
;                     } else {
;                         VPKMUL(px, P01, Rkk[c][0].xy); VPKFMA(px, P23, Rkk[c][0].zw, px); VPKFMA(px, P45, Rkk[c][1].xy, px); VPKFMA(px, P67, Rkk[c][1].zw, px);
;                         VADD(x, px.x, px.y);
;                     }
;                     asm volatile("" ::: "memory");
;                     if (s + 1 < 32) LOADREC((s + 1) & 1, s + 1);
;                     asm volatile("" ::: "memory");
;                     VPKMULBL(t01, vv2, Rkm[c][0].xy); VPKMULBL(t23, vv2, Rkm[c][0].zw);
;                     VDPP1(x); if (s >= 1) VDPP1(yp);
;                     VPKMULBL(t45, vv2, Rkm[c][1].xy); VPKMULBL(t67, vv2, Rkm[c][1].zw);
;                     VDPP2(x); if (s >= 1) VDPP2(yp);
;                     VPKFMA(P01, P01, Rw[c][0].xy, t01); VPKFMA(P23, P23, Rw[c][0].zw, t23);
;                     VDPP3(x); if (s >= 1) VDPP3(yp);
;                     VPKFMA(P45, P45, Rw[c][1].xy, t45); VPKFMA(P67, P67, Rw[c][1].zw, t67);
;                     if (s >= 1) { if (s - 1 < 8) YSHIFT(yk0); else if (s - 1 < 16) YSHIFT(yk1); else if (s - 1 < 24) YSHIFT(yk2); else YSHIFT(yk3); }
;                     x = x * si;
;                     f32x2 x2; x2.x = x; asm volatile("" : "+v"(x2));
	ds_read_b128 v[64:67], v35 offset:6256
	ds_read_b128 v[76:79], v35 offset:32368
	ds_read_b32 v94, v36 offset:2944
	ds_read_b32 v95, v38 offset:2944
	ds_read_b128 v[68:71], v35 offset:14960
	ds_read_b128 v[72:75], v35 offset:23664
	ds_read_b128 v[88:91], v35 offset:41072
	v_pk_mul_f32 v[8:9], v[0:1], v[48:49] op_sel_hi:[1,0]
	v_pk_mul_f32 v[10:11], v[0:1], v[80:81] op_sel_hi:[1,0]
	v_pk_fma_f32 v[8:9], v[2:3], v[48:49], v[8:9] op_sel:[0,1,0] op_sel_hi:[1,1,1]
	v_pk_fma_f32 v[10:11], v[2:3], v[80:81], v[10:11] op_sel:[0,1,0] op_sel_hi:[1,1,1]
	v_pk_fma_f32 v[8:9], v[4:5], v[50:51], v[8:9] op_sel_hi:[1,0,1]
	v_pk_fma_f32 v[10:11], v[4:5], v[82:83], v[10:11] op_sel_hi:[1,0,1]
	v_pk_fma_f32 v[8:9], v[6:7], v[50:51], v[8:9] op_sel:[0,1,0] op_sel_hi:[1,1,1]
	v_pk_fma_f32 v[10:11], v[6:7], v[82:83], v[10:11] op_sel:[0,1,0] op_sel_hi:[1,1,1]
	v_readlane_b32 s10, v34, 22
	v_pk_mul_f32 v[16:17], v[92:93], v[60:61] op_sel_hi:[1,0]
	v_pk_mul_f32 v[18:19], v[92:93], v[60:61] op_sel:[0,1] op_sel_hi:[1,1]
	v_add_f32_dpp v8, v9, v8 quad_perm:[1,0,3,2] row_mask:0xf bank_mask:0xf bound_ctrl:1
	v_add_f32_dpp v10, v11, v10 quad_perm:[1,0,3,2] row_mask:0xf bank_mask:0xf bound_ctrl:1
	v_pk_mul_f32 v[20:21], v[92:93], v[62:63] op_sel_hi:[1,0]
	v_pk_mul_f32 v[22:23], v[92:93], v[62:63] op_sel:[0,1] op_sel_hi:[1,1]
	v_add_f32_dpp v8, v8, v8 quad_perm:[2,3,0,1] row_mask:0xf bank_mask:0xf bound_ctrl:1
	v_add_f32_dpp v10, v10, v10 quad_perm:[2,3,0,1] row_mask:0xf bank_mask:0xf bound_ctrl:1
	v_pk_fma_f32 v[0:1], v[0:1], v[52:53], v[16:17] op_sel_hi:[1,0,1]
	v_pk_fma_f32 v[2:3], v[2:3], v[52:53], v[18:19] op_sel:[0,1,0] op_sel_hi:[1,1,1]
	v_add_f32_dpp v8, v8, v8 row_ror:4 row_mask:0xf bank_mask:0xf bound_ctrl:1
	v_add_f32_dpp v10, v10, v10 row_ror:4 row_mask:0xf bank_mask:0xf bound_ctrl:1
	v_pk_fma_f32 v[4:5], v[4:5], v[54:55], v[20:21] op_sel_hi:[1,0,1]
	v_add_f32_dpp v8, v8, v8 row_ror:8 row_mask:0xf bank_mask:0xf bound_ctrl:1
	v_mul_f32_e32 v8, s10, v8
	v_add_f32_dpp v101, v10, v10 row_ror:8 row_mask:0xf bank_mask:0x2 bound_ctrl:1
	v_pk_fma_f32 v[6:7], v[6:7], v[54:55], v[22:23] op_sel:[0,1,0] op_sel_hi:[1,1,1]
	v_mov_b32_dpp v9, v8 quad_perm:[1,0,3,2] row_mask:0xf bank_mask:0xf
	v_pk_fma_f32 v[0:1], v[8:9], v[56:57], v[0:1] op_sel_hi:[1,0,1] neg_lo:[1,0,0] neg_hi:[1,0,0]
	v_pk_fma_f32 v[2:3], v[8:9], v[56:57], v[2:3] op_sel:[0,1,0] op_sel_hi:[1,1,1] neg_lo:[1,0,0] neg_hi:[1,0,0]
	v_pk_fma_f32 v[4:5], v[8:9], v[58:59], v[4:5] op_sel_hi:[1,0,1] neg_lo:[1,0,0] neg_hi:[1,0,0]
	v_pk_fma_f32 v[6:7], v[8:9], v[58:59], v[6:7] op_sel:[0,1,0] op_sel_hi:[1,1,1] neg_lo:[1,0,0] neg_hi:[1,0,0]
	s_waitcnt lgkmcnt(0)
	ds_read_b128 v[48:51], v35 offset:6528
	ds_read_b128 v[60:63], v35 offset:32640
	ds_read_b32 v92, v36 offset:3072
	ds_read_b32 v93, v38 offset:3072
	ds_read_b128 v[52:55], v35 offset:15232
	ds_read_b128 v[56:59], v35 offset:23936
	ds_read_b128 v[80:83], v35 offset:41344
	v_pk_mul_f32 v[8:9], v[0:1], v[64:65] op_sel_hi:[1,0]
	v_pk_mul_f32 v[10:11], v[0:1], v[84:85] op_sel_hi:[1,0]
	v_pk_fma_f32 v[8:9], v[2:3], v[64:65], v[8:9] op_sel:[0,1,0] op_sel_hi:[1,1,1]
	v_pk_fma_f32 v[10:11], v[2:3], v[84:85], v[10:11] op_sel:[0,1,0] op_sel_hi:[1,1,1]
	v_pk_fma_f32 v[8:9], v[4:5], v[66:67], v[8:9] op_sel_hi:[1,0,1]
	v_pk_fma_f32 v[10:11], v[4:5], v[86:87], v[10:11] op_sel_hi:[1,0,1]
	v_pk_fma_f32 v[8:9], v[6:7], v[66:67], v[8:9] op_sel:[0,1,0] op_sel_hi:[1,1,1]
	v_pk_fma_f32 v[10:11], v[6:7], v[86:87], v[10:11] op_sel:[0,1,0] op_sel_hi:[1,1,1]
	v_readlane_b32 s10, v34, 23
	v_pk_mul_f32 v[16:17], v[94:95], v[76:77] op_sel_hi:[1,0]
	v_pk_mul_f32 v[18:19], v[94:95], v[76:77] op_sel:[0,1] op_sel_hi:[1,1]
	v_add_f32_dpp v8, v9, v8 quad_perm:[1,0,3,2] row_mask:0xf bank_mask:0xf bound_ctrl:1
	v_add_f32_dpp v10, v11, v10 quad_perm:[1,0,3,2] row_mask:0xf bank_mask:0xf bound_ctrl:1
	v_pk_mul_f32 v[20:21], v[94:95], v[78:79] op_sel_hi:[1,0]
	v_pk_mul_f32 v[22:23], v[94:95], v[78:79] op_sel:[0,1] op_sel_hi:[1,1]
	v_add_f32_dpp v8, v8, v8 quad_perm:[2,3,0,1] row_mask:0xf bank_mask:0xf bound_ctrl:1
	v_add_f32_dpp v10, v10, v10 quad_perm:[2,3,0,1] row_mask:0xf bank_mask:0xf bound_ctrl:1
	v_pk_fma_f32 v[0:1], v[0:1], v[68:69], v[16:17] op_sel_hi:[1,0,1]
	v_pk_fma_f32 v[2:3], v[2:3], v[68:69], v[18:19] op_sel:[0,1,0] op_sel_hi:[1,1,1]
	v_add_f32_dpp v8, v8, v8 row_ror:4 row_mask:0xf bank_mask:0xf bound_ctrl:1
	v_add_f32_dpp v10, v10, v10 row_ror:4 row_mask:0xf bank_mask:0xf bound_ctrl:1
	v_pk_fma_f32 v[4:5], v[4:5], v[70:71], v[20:21] op_sel_hi:[1,0,1]
	v_add_f32_dpp v8, v8, v8 row_ror:8 row_mask:0xf bank_mask:0xf bound_ctrl:1
	v_mul_f32_e32 v8, s10, v8
	v_add_f32_dpp v101, v10, v10 row_ror:8 row_mask:0xf bank_mask:0x4 bound_ctrl:1
	v_pk_fma_f32 v[6:7], v[6:7], v[70:71], v[22:23] op_sel:[0,1,0] op_sel_hi:[1,1,1]
	v_mov_b32_dpp v9, v8 quad_perm:[1,0,3,2] row_mask:0xf bank_mask:0xf
	v_pk_fma_f32 v[0:1], v[8:9], v[72:73], v[0:1] op_sel_hi:[1,0,1] neg_lo:[1,0,0] neg_hi:[1,0,0]
	v_pk_fma_f32 v[2:3], v[8:9], v[72:73], v[2:3] op_sel:[0,1,0] op_sel_hi:[1,1,1] neg_lo:[1,0,0] neg_hi:[1,0,0]
	v_pk_fma_f32 v[4:5], v[8:9], v[74:75], v[4:5] op_sel_hi:[1,0,1] neg_lo:[1,0,0] neg_hi:[1,0,0]
	v_pk_fma_f32 v[6:7], v[8:9], v[74:75], v[6:7] op_sel:[0,1,0] op_sel_hi:[1,1,1] neg_lo:[1,0,0] neg_hi:[1,0,0]
	s_waitcnt lgkmcnt(0)
; #define VPKMUL(d, a, b) asm volatile("v_pk_mul_f32 %0, %1, %2" : "=v"(d) : "v"(a), "v"(b))
; __device__ __forceinline__ void scan_half(const Params& p, LAS unsigned char* lds, int pi, int rh, int pass) {
;     ...
;                 LOADREC(0, 0);
;                 float yp = 0.f, yk0 = 0.f, yk1 = 0.f, yk2 = 0.f, yk3 = 0.f;
;     ...
; #pragma unroll
;                 for (int s = 0; s < 32; ++s) {
;                     const int c = s & 1, pc = c ^ 1;
;                     const float si = __int_as_float(__builtin_amdgcn_readlane(__float_as_int(inv2), s));
;                     f32x2 px, py, t01, t23, t45, t67; float x;
;                     f32x2 vv2; vv2.x = Rv[c]; asm volatile("" : "+v"(vv2));
;                     if (s >= 1) {
;                         VPKMUL(px, P01, Rkk[c][0].xy); VPKMUL(py, P01, Rr[pc][0].xy); VPKFMA(px, P23, Rkk[c][0].zw, px); VPKFMA(py, P23, Rr[pc][0].zw, py);
;                         VPKFMA(px, P45, Rkk[c][1].xy, px); VPKFMA(py, P45, Rr[pc][1].xy, py); VPKFMA(px, P67, Rkk[c][1].zw, px); VPKFMA(py, P67, Rr[pc][1].zw, py);
;                         VADD(x, px.x, px.y); VADD(yp, py.x, py.y);
;                     } else {
;                         VPKMUL(px, P01, Rkk[c][0].xy); VPKFMA(px, P23, Rkk[c][0].zw, px); VPKFMA(px, P45, Rkk[c][1].xy, px); VPKFMA(px, P67, Rkk[c][1].zw, px);
;                         VADD(x, px.x, px.y);
;                     }
;                     asm volatile("" ::: "memory");
;                     if (s + 1 < 32) LOADREC((s + 1) & 1, s + 1);
;                     asm volatile("" ::: "memory");
;                     VPKMULBL(t01, vv2, Rkm[c][0].xy); VPKMULBL(t23, vv2, Rkm[c][0].zw);
;                     VDPP1(x); if (s >= 1) VDPP1(yp);
;                     VPKMULBL(t45, vv2, Rkm[c][1].xy); VPKMULBL(t67, vv2, Rkm[c][1].zw);
;                     VDPP2(x); if (s >= 1) VDPP2(yp);
;                     VPKFMA(P01, P01, Rw[c][0].xy, t01); VPKFMA(P23, P23, Rw[c][0].zw, t23);
;                     VDPP3(x); if (s >= 1) VDPP3(yp);
;                     VPKFMA(P45, P45, Rw[c][1].xy, t45); VPKFMA(P67, P67, Rw[c][1].zw, t67);
;                     if (s >= 1) { if (s - 1 < 8) YSHIFT(yk0); else if (s - 1 < 16) YSHIFT(yk1); else if (s - 1 < 24) YSHIFT(yk2); else YSHIFT(yk3); }
;                     x = x * si;
;                     f32x2 x2; x2.x = x; asm volatile("" : "+v"(x2));
	ds_read_b128 v[64:67], v35 offset:6800
	ds_read_b128 v[76:79], v35 offset:32912
	ds_read_b32 v94, v36 offset:3200
	ds_read_b32 v95, v38 offset:3200
	ds_read_b128 v[68:71], v35 offset:15504
	ds_read_b128 v[72:75], v35 offset:24208
	ds_read_b128 v[84:87], v35 offset:41616
	v_pk_mul_f32 v[8:9], v[0:1], v[48:49] op_sel_hi:[1,0]
	v_pk_mul_f32 v[10:11], v[0:1], v[88:89] op_sel_hi:[1,0]
	v_pk_fma_f32 v[8:9], v[2:3], v[48:49], v[8:9] op_sel:[0,1,0] op_sel_hi:[1,1,1]
	v_pk_fma_f32 v[10:11], v[2:3], v[88:89], v[10:11] op_sel:[0,1,0] op_sel_hi:[1,1,1]
	v_pk_fma_f32 v[8:9], v[4:5], v[50:51], v[8:9] op_sel_hi:[1,0,1]
	v_pk_fma_f32 v[10:11], v[4:5], v[90:91], v[10:11] op_sel_hi:[1,0,1]
	v_pk_fma_f32 v[8:9], v[6:7], v[50:51], v[8:9] op_sel:[0,1,0] op_sel_hi:[1,1,1]
	v_pk_fma_f32 v[10:11], v[6:7], v[90:91], v[10:11] op_sel:[0,1,0] op_sel_hi:[1,1,1]
	v_readlane_b32 s10, v34, 24
	v_pk_mul_f32 v[16:17], v[92:93], v[60:61] op_sel_hi:[1,0]
	v_pk_mul_f32 v[18:19], v[92:93], v[60:61] op_sel:[0,1] op_sel_hi:[1,1]
	v_add_f32_dpp v8, v9, v8 quad_perm:[1,0,3,2] row_mask:0xf bank_mask:0xf bound_ctrl:1
	v_add_f32_dpp v10, v11, v10 quad_perm:[1,0,3,2] row_mask:0xf bank_mask:0xf bound_ctrl:1
	v_pk_mul_f32 v[20:21], v[92:93], v[62:63] op_sel_hi:[1,0]
	v_pk_mul_f32 v[22:23], v[92:93], v[62:63] op_sel:[0,1] op_sel_hi:[1,1]
	v_add_f32_dpp v8, v8, v8 quad_perm:[2,3,0,1] row_mask:0xf bank_mask:0xf bound_ctrl:1
	v_add_f32_dpp v10, v10, v10 quad_perm:[2,3,0,1] row_mask:0xf bank_mask:0xf bound_ctrl:1
	v_pk_fma_f32 v[0:1], v[0:1], v[52:53], v[16:17] op_sel_hi:[1,0,1]
	v_pk_fma_f32 v[2:3], v[2:3], v[52:53], v[18:19] op_sel:[0,1,0] op_sel_hi:[1,1,1]
	v_add_f32_dpp v8, v8, v8 row_ror:4 row_mask:0xf bank_mask:0xf bound_ctrl:1
	v_add_f32_dpp v10, v10, v10 row_ror:4 row_mask:0xf bank_mask:0xf bound_ctrl:1
	v_pk_fma_f32 v[4:5], v[4:5], v[54:55], v[20:21] op_sel_hi:[1,0,1]
	v_add_f32_dpp v8, v8, v8 row_ror:8 row_mask:0xf bank_mask:0xf bound_ctrl:1
	v_mul_f32_e32 v8, s10, v8
	v_add_f32_dpp v101, v10, v10 row_ror:8 row_mask:0xf bank_mask:0x8 bound_ctrl:1
	v_pk_fma_f32 v[6:7], v[6:7], v[54:55], v[22:23] op_sel:[0,1,0] op_sel_hi:[1,1,1]
	v_mov_b32_dpp v9, v8 quad_perm:[1,0,3,2] row_mask:0xf bank_mask:0xf
	v_pk_fma_f32 v[0:1], v[8:9], v[56:57], v[0:1] op_sel_hi:[1,0,1] neg_lo:[1,0,0] neg_hi:[1,0,0]
	v_pk_fma_f32 v[2:3], v[8:9], v[56:57], v[2:3] op_sel:[0,1,0] op_sel_hi:[1,1,1] neg_lo:[1,0,0] neg_hi:[1,0,0]
	v_pk_fma_f32 v[4:5], v[8:9], v[58:59], v[4:5] op_sel_hi:[1,0,1] neg_lo:[1,0,0] neg_hi:[1,0,0]
	v_pk_fma_f32 v[6:7], v[8:9], v[58:59], v[6:7] op_sel:[0,1,0] op_sel_hi:[1,1,1] neg_lo:[1,0,0] neg_hi:[1,0,0]
	s_waitcnt lgkmcnt(0)
	ds_read_b128 v[48:51], v35 offset:7072
	ds_read_b128 v[60:63], v35 offset:33184
	ds_read_b32 v92, v36 offset:3328
	ds_read_b32 v93, v38 offset:3328
	ds_read_b128 v[52:55], v35 offset:15776
	ds_read_b128 v[56:59], v35 offset:24480
	ds_read_b128 v[88:91], v35 offset:41888
	v_pk_mul_f32 v[8:9], v[0:1], v[64:65] op_sel_hi:[1,0]
	v_pk_mul_f32 v[10:11], v[0:1], v[80:81] op_sel_hi:[1,0]
	v_pk_fma_f32 v[8:9], v[2:3], v[64:65], v[8:9] op_sel:[0,1,0] op_sel_hi:[1,1,1]
	v_pk_fma_f32 v[10:11], v[2:3], v[80:81], v[10:11] op_sel:[0,1,0] op_sel_hi:[1,1,1]
	v_pk_fma_f32 v[8:9], v[4:5], v[66:67], v[8:9] op_sel_hi:[1,0,1]
	v_pk_fma_f32 v[10:11], v[4:5], v[82:83], v[10:11] op_sel_hi:[1,0,1]
	v_pk_fma_f32 v[8:9], v[6:7], v[66:67], v[8:9] op_sel:[0,1,0] op_sel_hi:[1,1,1]
	v_pk_fma_f32 v[10:11], v[6:7], v[82:83], v[10:11] op_sel:[0,1,0] op_sel_hi:[1,1,1]
	v_readlane_b32 s10, v34, 25
	v_pk_mul_f32 v[16:17], v[94:95], v[76:77] op_sel_hi:[1,0]
	v_pk_mul_f32 v[18:19], v[94:95], v[76:77] op_sel:[0,1] op_sel_hi:[1,1]
	v_add_f32_dpp v8, v9, v8 quad_perm:[1,0,3,2] row_mask:0xf bank_mask:0xf bound_ctrl:1
	v_add_f32_dpp v10, v11, v10 quad_perm:[1,0,3,2] row_mask:0xf bank_mask:0xf bound_ctrl:1
	v_pk_mul_f32 v[20:21], v[94:95], v[78:79] op_sel_hi:[1,0]
	v_pk_mul_f32 v[22:23], v[94:95], v[78:79] op_sel:[0,1] op_sel_hi:[1,1]
	v_add_f32_dpp v8, v8, v8 quad_perm:[2,3,0,1] row_mask:0xf bank_mask:0xf bound_ctrl:1
	v_add_f32_dpp v10, v10, v10 quad_perm:[2,3,0,1] row_mask:0xf bank_mask:0xf bound_ctrl:1
	v_pk_fma_f32 v[0:1], v[0:1], v[68:69], v[16:17] op_sel_hi:[1,0,1]
	v_pk_fma_f32 v[2:3], v[2:3], v[68:69], v[18:19] op_sel:[0,1,0] op_sel_hi:[1,1,1]
	v_add_f32_dpp v8, v8, v8 row_ror:4 row_mask:0xf bank_mask:0xf bound_ctrl:1
	v_add_f32_dpp v10, v10, v10 row_ror:4 row_mask:0xf bank_mask:0xf bound_ctrl:1
	v_pk_fma_f32 v[4:5], v[4:5], v[70:71], v[20:21] op_sel_hi:[1,0,1]
	v_add_f32_dpp v8, v8, v8 row_ror:8 row_mask:0xf bank_mask:0xf bound_ctrl:1
	v_mul_f32_e32 v8, s10, v8
	v_add_f32_dpp v102, v10, v10 row_ror:8 row_mask:0xf bank_mask:0x1 bound_ctrl:1
	v_pk_fma_f32 v[6:7], v[6:7], v[70:71], v[22:23] op_sel:[0,1,0] op_sel_hi:[1,1,1]
	v_mov_b32_dpp v9, v8 quad_perm:[1,0,3,2] row_mask:0xf bank_mask:0xf
	v_pk_fma_f32 v[0:1], v[8:9], v[72:73], v[0:1] op_sel_hi:[1,0,1] neg_lo:[1,0,0] neg_hi:[1,0,0]
	v_pk_fma_f32 v[2:3], v[8:9], v[72:73], v[2:3] op_sel:[0,1,0] op_sel_hi:[1,1,1] neg_lo:[1,0,0] neg_hi:[1,0,0]
	v_pk_fma_f32 v[4:5], v[8:9], v[74:75], v[4:5] op_sel_hi:[1,0,1] neg_lo:[1,0,0] neg_hi:[1,0,0]
	v_pk_fma_f32 v[6:7], v[8:9], v[74:75], v[6:7] op_sel:[0,1,0] op_sel_hi:[1,1,1] neg_lo:[1,0,0] neg_hi:[1,0,0]
	s_waitcnt lgkmcnt(0)
; #define VPKMUL(d, a, b) asm volatile("v_pk_mul_f32 %0, %1, %2" : "=v"(d) : "v"(a), "v"(b))
; __device__ __forceinline__ void scan_half(const Params& p, LAS unsigned char* lds, int pi, int rh, int pass) {
;     ...
;                 LOADREC(0, 0);
;                 float yp = 0.f, yk0 = 0.f, yk1 = 0.f, yk2 = 0.f, yk3 = 0.f;
;     ...
; #pragma unroll
;                 for (int s = 0; s < 32; ++s) {
;                     const int c = s & 1, pc = c ^ 1;
;                     const float si = __int_as_float(__builtin_amdgcn_readlane(__float_as_int(inv2), s));
;                     f32x2 px, py, t01, t23, t45, t67; float x;
;                     f32x2 vv2; vv2.x = Rv[c]; asm volatile("" : "+v"(vv2));
;                     if (s >= 1) {
;                         VPKMUL(px, P01, Rkk[c][0].xy); VPKMUL(py, P01, Rr[pc][0].xy); VPKFMA(px, P23, Rkk[c][0].zw, px); VPKFMA(py, P23, Rr[pc][0].zw, py);
;                         VPKFMA(px, P45, Rkk[c][1].xy, px); VPKFMA(py, P45, Rr[pc][1].xy, py); VPKFMA(px, P67, Rkk[c][1].zw, px); VPKFMA(py, P67, Rr[pc][1].zw, py);
;                         VADD(x, px.x, px.y); VADD(yp, py.x, py.y);
;                     } else {
;                         VPKMUL(px, P01, Rkk[c][0].xy); VPKFMA(px, P23, Rkk[c][0].zw, px); VPKFMA(px, P45, Rkk[c][1].xy, px); VPKFMA(px, P67, Rkk[c][1].zw, px);
;                         VADD(x, px.x, px.y);
;                     }
;                     asm volatile("" ::: "memory");
;                     if (s + 1 < 32) LOADREC((s + 1) & 1, s + 1);
;                     asm volatile("" ::: "memory");
;                     VPKMULBL(t01, vv2, Rkm[c][0].xy); VPKMULBL(t23, vv2, Rkm[c][0].zw);
;                     VDPP1(x); if (s >= 1) VDPP1(yp);
;                     VPKMULBL(t45, vv2, Rkm[c][1].xy); VPKMULBL(t67, vv2, Rkm[c][1].zw);
;                     VDPP2(x); if (s >= 1) VDPP2(yp);
;                     VPKFMA(P01, P01, Rw[c][0].xy, t01); VPKFMA(P23, P23, Rw[c][0].zw, t23);
;                     VDPP3(x); if (s >= 1) VDPP3(yp);
;                     VPKFMA(P45, P45, Rw[c][1].xy, t45); VPKFMA(P67, P67, Rw[c][1].zw, t67);
;                     if (s >= 1) { if (s - 1 < 8) YSHIFT(yk0); else if (s - 1 < 16) YSHIFT(yk1); else if (s - 1 < 24) YSHIFT(yk2); else YSHIFT(yk3); }
;                     x = x * si;
;                     f32x2 x2; x2.x = x; asm volatile("" : "+v"(x2));
	ds_read_b128 v[64:67], v35 offset:7344
	ds_read_b128 v[76:79], v35 offset:33456
	ds_read_b32 v94, v36 offset:3456
	ds_read_b32 v95, v38 offset:3456
	ds_read_b128 v[68:71], v35 offset:16048
	ds_read_b128 v[72:75], v35 offset:24752
	ds_read_b128 v[80:83], v35 offset:42160
	v_pk_mul_f32 v[8:9], v[0:1], v[48:49] op_sel_hi:[1,0]
	v_pk_mul_f32 v[10:11], v[0:1], v[84:85] op_sel_hi:[1,0]
	v_pk_fma_f32 v[8:9], v[2:3], v[48:49], v[8:9] op_sel:[0,1,0] op_sel_hi:[1,1,1]
	v_pk_fma_f32 v[10:11], v[2:3], v[84:85], v[10:11] op_sel:[0,1,0] op_sel_hi:[1,1,1]
	v_pk_fma_f32 v[8:9], v[4:5], v[50:51], v[8:9] op_sel_hi:[1,0,1]
	v_pk_fma_f32 v[10:11], v[4:5], v[86:87], v[10:11] op_sel_hi:[1,0,1]
	v_pk_fma_f32 v[8:9], v[6:7], v[50:51], v[8:9] op_sel:[0,1,0] op_sel_hi:[1,1,1]
	v_pk_fma_f32 v[10:11], v[6:7], v[86:87], v[10:11] op_sel:[0,1,0] op_sel_hi:[1,1,1]
	v_readlane_b32 s10, v34, 26
	v_pk_mul_f32 v[16:17], v[92:93], v[60:61] op_sel_hi:[1,0]
	v_pk_mul_f32 v[18:19], v[92:93], v[60:61] op_sel:[0,1] op_sel_hi:[1,1]
	v_add_f32_dpp v8, v9, v8 quad_perm:[1,0,3,2] row_mask:0xf bank_mask:0xf bound_ctrl:1
	v_add_f32_dpp v10, v11, v10 quad_perm:[1,0,3,2] row_mask:0xf bank_mask:0xf bound_ctrl:1
	v_pk_mul_f32 v[20:21], v[92:93], v[62:63] op_sel_hi:[1,0]
	v_pk_mul_f32 v[22:23], v[92:93], v[62:63] op_sel:[0,1] op_sel_hi:[1,1]
	v_add_f32_dpp v8, v8, v8 quad_perm:[2,3,0,1] row_mask:0xf bank_mask:0xf bound_ctrl:1
	v_add_f32_dpp v10, v10, v10 quad_perm:[2,3,0,1] row_mask:0xf bank_mask:0xf bound_ctrl:1
	v_pk_fma_f32 v[0:1], v[0:1], v[52:53], v[16:17] op_sel_hi:[1,0,1]
	v_pk_fma_f32 v[2:3], v[2:3], v[52:53], v[18:19] op_sel:[0,1,0] op_sel_hi:[1,1,1]
	v_add_f32_dpp v8, v8, v8 row_ror:4 row_mask:0xf bank_mask:0xf bound_ctrl:1
	v_add_f32_dpp v10, v10, v10 row_ror:4 row_mask:0xf bank_mask:0xf bound_ctrl:1
	v_pk_fma_f32 v[4:5], v[4:5], v[54:55], v[20:21] op_sel_hi:[1,0,1]
	v_add_f32_dpp v8, v8, v8 row_ror:8 row_mask:0xf bank_mask:0xf bound_ctrl:1
	v_mul_f32_e32 v8, s10, v8
	v_add_f32_dpp v102, v10, v10 row_ror:8 row_mask:0xf bank_mask:0x2 bound_ctrl:1
	v_pk_fma_f32 v[6:7], v[6:7], v[54:55], v[22:23] op_sel:[0,1,0] op_sel_hi:[1,1,1]
	v_mov_b32_dpp v9, v8 quad_perm:[1,0,3,2] row_mask:0xf bank_mask:0xf
	v_pk_fma_f32 v[0:1], v[8:9], v[56:57], v[0:1] op_sel_hi:[1,0,1] neg_lo:[1,0,0] neg_hi:[1,0,0]
	v_pk_fma_f32 v[2:3], v[8:9], v[56:57], v[2:3] op_sel:[0,1,0] op_sel_hi:[1,1,1] neg_lo:[1,0,0] neg_hi:[1,0,0]
	v_pk_fma_f32 v[4:5], v[8:9], v[58:59], v[4:5] op_sel_hi:[1,0,1] neg_lo:[1,0,0] neg_hi:[1,0,0]
	v_pk_fma_f32 v[6:7], v[8:9], v[58:59], v[6:7] op_sel:[0,1,0] op_sel_hi:[1,1,1] neg_lo:[1,0,0] neg_hi:[1,0,0]
	s_waitcnt lgkmcnt(0)
	ds_read_b128 v[48:51], v35 offset:7616
	ds_read_b128 v[60:63], v35 offset:33728
	ds_read_b32 v92, v36 offset:3584
	ds_read_b32 v93, v38 offset:3584
	ds_read_b128 v[52:55], v35 offset:16320
	ds_read_b128 v[56:59], v35 offset:25024
	ds_read_b128 v[84:87], v35 offset:42432
	v_pk_mul_f32 v[8:9], v[0:1], v[64:65] op_sel_hi:[1,0]
	v_pk_mul_f32 v[10:11], v[0:1], v[88:89] op_sel_hi:[1,0]
	v_pk_fma_f32 v[8:9], v[2:3], v[64:65], v[8:9] op_sel:[0,1,0] op_sel_hi:[1,1,1]
	v_pk_fma_f32 v[10:11], v[2:3], v[88:89], v[10:11] op_sel:[0,1,0] op_sel_hi:[1,1,1]
	v_pk_fma_f32 v[8:9], v[4:5], v[66:67], v[8:9] op_sel_hi:[1,0,1]
	v_pk_fma_f32 v[10:11], v[4:5], v[90:91], v[10:11] op_sel_hi:[1,0,1]
	v_pk_fma_f32 v[8:9], v[6:7], v[66:67], v[8:9] op_sel:[0,1,0] op_sel_hi:[1,1,1]
	v_pk_fma_f32 v[10:11], v[6:7], v[90:91], v[10:11] op_sel:[0,1,0] op_sel_hi:[1,1,1]
	v_readlane_b32 s10, v34, 27
	v_pk_mul_f32 v[16:17], v[94:95], v[76:77] op_sel_hi:[1,0]
	v_pk_mul_f32 v[18:19], v[94:95], v[76:77] op_sel:[0,1] op_sel_hi:[1,1]
	v_add_f32_dpp v8, v9, v8 quad_perm:[1,0,3,2] row_mask:0xf bank_mask:0xf bound_ctrl:1
	v_add_f32_dpp v10, v11, v10 quad_perm:[1,0,3,2] row_mask:0xf bank_mask:0xf bound_ctrl:1
	v_pk_mul_f32 v[20:21], v[94:95], v[78:79] op_sel_hi:[1,0]
	v_pk_mul_f32 v[22:23], v[94:95], v[78:79] op_sel:[0,1] op_sel_hi:[1,1]
	v_add_f32_dpp v8, v8, v8 quad_perm:[2,3,0,1] row_mask:0xf bank_mask:0xf bound_ctrl:1
	v_add_f32_dpp v10, v10, v10 quad_perm:[2,3,0,1] row_mask:0xf bank_mask:0xf bound_ctrl:1
	v_pk_fma_f32 v[0:1], v[0:1], v[68:69], v[16:17] op_sel_hi:[1,0,1]
	v_pk_fma_f32 v[2:3], v[2:3], v[68:69], v[18:19] op_sel:[0,1,0] op_sel_hi:[1,1,1]
	v_add_f32_dpp v8, v8, v8 row_ror:4 row_mask:0xf bank_mask:0xf bound_ctrl:1
	v_add_f32_dpp v10, v10, v10 row_ror:4 row_mask:0xf bank_mask:0xf bound_ctrl:1
	v_pk_fma_f32 v[4:5], v[4:5], v[70:71], v[20:21] op_sel_hi:[1,0,1]
	v_add_f32_dpp v8, v8, v8 row_ror:8 row_mask:0xf bank_mask:0xf bound_ctrl:1
	v_mul_f32_e32 v8, s10, v8
	v_add_f32_dpp v102, v10, v10 row_ror:8 row_mask:0xf bank_mask:0x4 bound_ctrl:1
	v_pk_fma_f32 v[6:7], v[6:7], v[70:71], v[22:23] op_sel:[0,1,0] op_sel_hi:[1,1,1]
	v_mov_b32_dpp v9, v8 quad_perm:[1,0,3,2] row_mask:0xf bank_mask:0xf
	v_pk_fma_f32 v[0:1], v[8:9], v[72:73], v[0:1] op_sel_hi:[1,0,1] neg_lo:[1,0,0] neg_hi:[1,0,0]
	v_pk_fma_f32 v[2:3], v[8:9], v[72:73], v[2:3] op_sel:[0,1,0] op_sel_hi:[1,1,1] neg_lo:[1,0,0] neg_hi:[1,0,0]
	v_pk_fma_f32 v[4:5], v[8:9], v[74:75], v[4:5] op_sel_hi:[1,0,1] neg_lo:[1,0,0] neg_hi:[1,0,0]
	v_pk_fma_f32 v[6:7], v[8:9], v[74:75], v[6:7] op_sel:[0,1,0] op_sel_hi:[1,1,1] neg_lo:[1,0,0] neg_hi:[1,0,0]
	s_waitcnt lgkmcnt(0)
; #define VPKMUL(d, a, b) asm volatile("v_pk_mul_f32 %0, %1, %2" : "=v"(d) : "v"(a), "v"(b))
; __device__ __forceinline__ void scan_half(const Params& p, LAS unsigned char* lds, int pi, int rh, int pass) {
;     ...
;                 LOADREC(0, 0);
;                 float yp = 0.f, yk0 = 0.f, yk1 = 0.f, yk2 = 0.f, yk3 = 0.f;
;     ...
; #pragma unroll
;                 for (int s = 0; s < 32; ++s) {
;                     const int c = s & 1, pc = c ^ 1;
;                     const float si = __int_as_float(__builtin_amdgcn_readlane(__float_as_int(inv2), s));
;                     f32x2 px, py, t01, t23, t45, t67; float x;
;                     f32x2 vv2; vv2.x = Rv[c]; asm volatile("" : "+v"(vv2));
;                     if (s >= 1) {
;                         VPKMUL(px, P01, Rkk[c][0].xy); VPKMUL(py, P01, Rr[pc][0].xy); VPKFMA(px, P23, Rkk[c][0].zw, px); VPKFMA(py, P23, Rr[pc][0].zw, py);
;                         VPKFMA(px, P45, Rkk[c][1].xy, px); VPKFMA(py, P45, Rr[pc][1].xy, py); VPKFMA(px, P67, Rkk[c][1].zw, px); VPKFMA(py, P67, Rr[pc][1].zw, py);
;                         VADD(x, px.x, px.y); VADD(yp, py.x, py.y);
;                     } else {
;                         VPKMUL(px, P01, Rkk[c][0].xy); VPKFMA(px, P23, Rkk[c][0].zw, px); VPKFMA(px, P45, Rkk[c][1].xy, px); VPKFMA(px, P67, Rkk[c][1].zw, px);
;                         VADD(x, px.x, px.y);
;                     }
;                     asm volatile("" ::: "memory");
;                     if (s + 1 < 32) LOADREC((s + 1) & 1, s + 1);
;                     asm volatile("" ::: "memory");
;                     VPKMULBL(t01, vv2, Rkm[c][0].xy); VPKMULBL(t23, vv2, Rkm[c][0].zw);
;                     VDPP1(x); if (s >= 1) VDPP1(yp);
;                     VPKMULBL(t45, vv2, Rkm[c][1].xy); VPKMULBL(t67, vv2, Rkm[c][1].zw);
;                     VDPP2(x); if (s >= 1) VDPP2(yp);
;                     VPKFMA(P01, P01, Rw[c][0].xy, t01); VPKFMA(P23, P23, Rw[c][0].zw, t23);
;                     VDPP3(x); if (s >= 1) VDPP3(yp);
;                     VPKFMA(P45, P45, Rw[c][1].xy, t45); VPKFMA(P67, P67, Rw[c][1].zw, t67);
;                     if (s >= 1) { if (s - 1 < 8) YSHIFT(yk0); else if (s - 1 < 16) YSHIFT(yk1); else if (s - 1 < 24) YSHIFT(yk2); else YSHIFT(yk3); }
;                     x = x * si;
;                     f32x2 x2; x2.x = x; asm volatile("" : "+v"(x2));
	ds_read_b128 v[64:67], v35 offset:7888
	ds_read_b128 v[76:79], v35 offset:34000
	ds_read_b32 v94, v36 offset:3712
	ds_read_b32 v95, v38 offset:3712
	ds_read_b128 v[68:71], v35 offset:16592
	ds_read_b128 v[72:75], v35 offset:25296
	ds_read_b128 v[88:91], v35 offset:42704
	v_pk_mul_f32 v[8:9], v[0:1], v[48:49] op_sel_hi:[1,0]
	v_pk_mul_f32 v[10:11], v[0:1], v[80:81] op_sel_hi:[1,0]
	v_pk_fma_f32 v[8:9], v[2:3], v[48:49], v[8:9] op_sel:[0,1,0] op_sel_hi:[1,1,1]
	v_pk_fma_f32 v[10:11], v[2:3], v[80:81], v[10:11] op_sel:[0,1,0] op_sel_hi:[1,1,1]
	v_pk_fma_f32 v[8:9], v[4:5], v[50:51], v[8:9] op_sel_hi:[1,0,1]
	v_pk_fma_f32 v[10:11], v[4:5], v[82:83], v[10:11] op_sel_hi:[1,0,1]
	v_pk_fma_f32 v[8:9], v[6:7], v[50:51], v[8:9] op_sel:[0,1,0] op_sel_hi:[1,1,1]
	v_pk_fma_f32 v[10:11], v[6:7], v[82:83], v[10:11] op_sel:[0,1,0] op_sel_hi:[1,1,1]
	v_readlane_b32 s10, v34, 28
	v_pk_mul_f32 v[16:17], v[92:93], v[60:61] op_sel_hi:[1,0]
	v_pk_mul_f32 v[18:19], v[92:93], v[60:61] op_sel:[0,1] op_sel_hi:[1,1]
	v_add_f32_dpp v8, v9, v8 quad_perm:[1,0,3,2] row_mask:0xf bank_mask:0xf bound_ctrl:1
	v_add_f32_dpp v10, v11, v10 quad_perm:[1,0,3,2] row_mask:0xf bank_mask:0xf bound_ctrl:1
	v_pk_mul_f32 v[20:21], v[92:93], v[62:63] op_sel_hi:[1,0]
	v_pk_mul_f32 v[22:23], v[92:93], v[62:63] op_sel:[0,1] op_sel_hi:[1,1]
	v_add_f32_dpp v8, v8, v8 quad_perm:[2,3,0,1] row_mask:0xf bank_mask:0xf bound_ctrl:1
	v_add_f32_dpp v10, v10, v10 quad_perm:[2,3,0,1] row_mask:0xf bank_mask:0xf bound_ctrl:1
	v_pk_fma_f32 v[0:1], v[0:1], v[52:53], v[16:17] op_sel_hi:[1,0,1]
	v_pk_fma_f32 v[2:3], v[2:3], v[52:53], v[18:19] op_sel:[0,1,0] op_sel_hi:[1,1,1]
	v_add_f32_dpp v8, v8, v8 row_ror:4 row_mask:0xf bank_mask:0xf bound_ctrl:1
	v_add_f32_dpp v10, v10, v10 row_ror:4 row_mask:0xf bank_mask:0xf bound_ctrl:1
	v_pk_fma_f32 v[4:5], v[4:5], v[54:55], v[20:21] op_sel_hi:[1,0,1]
	v_add_f32_dpp v8, v8, v8 row_ror:8 row_mask:0xf bank_mask:0xf bound_ctrl:1
	v_mul_f32_e32 v8, s10, v8
	v_add_f32_dpp v102, v10, v10 row_ror:8 row_mask:0xf bank_mask:0x8 bound_ctrl:1
	v_pk_fma_f32 v[6:7], v[6:7], v[54:55], v[22:23] op_sel:[0,1,0] op_sel_hi:[1,1,1]
	v_mov_b32_dpp v9, v8 quad_perm:[1,0,3,2] row_mask:0xf bank_mask:0xf
	v_pk_fma_f32 v[0:1], v[8:9], v[56:57], v[0:1] op_sel_hi:[1,0,1] neg_lo:[1,0,0] neg_hi:[1,0,0]
	v_pk_fma_f32 v[2:3], v[8:9], v[56:57], v[2:3] op_sel:[0,1,0] op_sel_hi:[1,1,1] neg_lo:[1,0,0] neg_hi:[1,0,0]
	v_pk_fma_f32 v[4:5], v[8:9], v[58:59], v[4:5] op_sel_hi:[1,0,1] neg_lo:[1,0,0] neg_hi:[1,0,0]
	v_pk_fma_f32 v[6:7], v[8:9], v[58:59], v[6:7] op_sel:[0,1,0] op_sel_hi:[1,1,1] neg_lo:[1,0,0] neg_hi:[1,0,0]
	s_waitcnt lgkmcnt(0)
	ds_read_b128 v[48:51], v35 offset:8160
	ds_read_b128 v[60:63], v35 offset:34272
	ds_read_b32 v92, v36 offset:3840
	ds_read_b32 v93, v38 offset:3840
	ds_read_b128 v[52:55], v35 offset:16864
	ds_read_b128 v[56:59], v35 offset:25568
	ds_read_b128 v[80:83], v35 offset:42976
	v_pk_mul_f32 v[8:9], v[0:1], v[64:65] op_sel_hi:[1,0]
	v_pk_mul_f32 v[10:11], v[0:1], v[84:85] op_sel_hi:[1,0]
	v_pk_fma_f32 v[8:9], v[2:3], v[64:65], v[8:9] op_sel:[0,1,0] op_sel_hi:[1,1,1]
	v_pk_fma_f32 v[10:11], v[2:3], v[84:85], v[10:11] op_sel:[0,1,0] op_sel_hi:[1,1,1]
	v_pk_fma_f32 v[8:9], v[4:5], v[66:67], v[8:9] op_sel_hi:[1,0,1]
	v_pk_fma_f32 v[10:11], v[4:5], v[86:87], v[10:11] op_sel_hi:[1,0,1]
	v_pk_fma_f32 v[8:9], v[6:7], v[66:67], v[8:9] op_sel:[0,1,0] op_sel_hi:[1,1,1]
	v_pk_fma_f32 v[10:11], v[6:7], v[86:87], v[10:11] op_sel:[0,1,0] op_sel_hi:[1,1,1]
	v_readlane_b32 s10, v34, 29
	v_pk_mul_f32 v[16:17], v[94:95], v[76:77] op_sel_hi:[1,0]
	v_pk_mul_f32 v[18:19], v[94:95], v[76:77] op_sel:[0,1] op_sel_hi:[1,1]
	v_add_f32_dpp v8, v9, v8 quad_perm:[1,0,3,2] row_mask:0xf bank_mask:0xf bound_ctrl:1
	v_add_f32_dpp v10, v11, v10 quad_perm:[1,0,3,2] row_mask:0xf bank_mask:0xf bound_ctrl:1
	v_pk_mul_f32 v[20:21], v[94:95], v[78:79] op_sel_hi:[1,0]
	v_pk_mul_f32 v[22:23], v[94:95], v[78:79] op_sel:[0,1] op_sel_hi:[1,1]
	v_add_f32_dpp v8, v8, v8 quad_perm:[2,3,0,1] row_mask:0xf bank_mask:0xf bound_ctrl:1
	v_add_f32_dpp v10, v10, v10 quad_perm:[2,3,0,1] row_mask:0xf bank_mask:0xf bound_ctrl:1
	v_pk_fma_f32 v[0:1], v[0:1], v[68:69], v[16:17] op_sel_hi:[1,0,1]
	v_pk_fma_f32 v[2:3], v[2:3], v[68:69], v[18:19] op_sel:[0,1,0] op_sel_hi:[1,1,1]
	v_add_f32_dpp v8, v8, v8 row_ror:4 row_mask:0xf bank_mask:0xf bound_ctrl:1
	v_add_f32_dpp v10, v10, v10 row_ror:4 row_mask:0xf bank_mask:0xf bound_ctrl:1
	v_pk_fma_f32 v[4:5], v[4:5], v[70:71], v[20:21] op_sel_hi:[1,0,1]
	v_add_f32_dpp v8, v8, v8 row_ror:8 row_mask:0xf bank_mask:0xf bound_ctrl:1
	v_mul_f32_e32 v8, s10, v8
	v_add_f32_dpp v103, v10, v10 row_ror:8 row_mask:0xf bank_mask:0x1 bound_ctrl:1
	v_pk_fma_f32 v[6:7], v[6:7], v[70:71], v[22:23] op_sel:[0,1,0] op_sel_hi:[1,1,1]
	v_mov_b32_dpp v9, v8 quad_perm:[1,0,3,2] row_mask:0xf bank_mask:0xf
	v_pk_fma_f32 v[0:1], v[8:9], v[72:73], v[0:1] op_sel_hi:[1,0,1] neg_lo:[1,0,0] neg_hi:[1,0,0]
	v_pk_fma_f32 v[2:3], v[8:9], v[72:73], v[2:3] op_sel:[0,1,0] op_sel_hi:[1,1,1] neg_lo:[1,0,0] neg_hi:[1,0,0]
	v_pk_fma_f32 v[4:5], v[8:9], v[74:75], v[4:5] op_sel_hi:[1,0,1] neg_lo:[1,0,0] neg_hi:[1,0,0]
	v_pk_fma_f32 v[6:7], v[8:9], v[74:75], v[6:7] op_sel:[0,1,0] op_sel_hi:[1,1,1] neg_lo:[1,0,0] neg_hi:[1,0,0]
	s_waitcnt lgkmcnt(0)
; __device__ __forceinline__ void scan_half(const Params& p, LAS unsigned char* lds, int pi, int rh, int pass) {
;     ...
;                 for (int s = 0; s < 32; ++s) {
;                     const int c = s & 1, pc = c ^ 1;
;                     const float si = __int_as_float(__builtin_amdgcn_readlane(__float_as_int(inv2), s));
;                     f32x2 px, py, t01, t23, t45, t67; float x;
;                     f32x2 vv2; vv2.x = Rv[c]; asm volatile("" : "+v"(vv2));
;                     if (s >= 1) {
;                         VPKMUL(px, P01, Rkk[c][0].xy); VPKMUL(py, P01, Rr[pc][0].xy); VPKFMA(px, P23, Rkk[c][0].zw, px); VPKFMA(py, P23, Rr[pc][0].zw, py);
;                         VPKFMA(px, P45, Rkk[c][1].xy, px); VPKFMA(py, P45, Rr[pc][1].xy, py); VPKFMA(px, P67, Rkk[c][1].zw, px); VPKFMA(py, P67, Rr[pc][1].zw, py);
;                         VADD(x, px.x, px.y); VADD(yp, py.x, py.y);
;                     } else {
;                         VPKMUL(px, P01, Rkk[c][0].xy); VPKFMA(px, P23, Rkk[c][0].zw, px); VPKFMA(px, P45, Rkk[c][1].xy, px); VPKFMA(px, P67, Rkk[c][1].zw, px);
;                         VADD(x, px.x, px.y);
;                     }
;                     asm volatile("" ::: "memory");
;                     if (s + 1 < 32) LOADREC((s + 1) & 1, s + 1);
;                     asm volatile("" ::: "memory");
;                     VPKMULBL(t01, vv2, Rkm[c][0].xy); VPKMULBL(t23, vv2, Rkm[c][0].zw);
;                     VDPP1(x); if (s >= 1) VDPP1(yp);
;                     VPKMULBL(t45, vv2, Rkm[c][1].xy); VPKMULBL(t67, vv2, Rkm[c][1].zw);
;                     VDPP2(x); if (s >= 1) VDPP2(yp);
;                     VPKFMA(P01, P01, Rw[c][0].xy, t01); VPKFMA(P23, P23, Rw[c][0].zw, t23);
;                     VDPP3(x); if (s >= 1) VDPP3(yp);
;                     VPKFMA(P45, P45, Rw[c][1].xy, t45); VPKFMA(P67, P67, Rw[c][1].zw, t67);
;                     if (s >= 1) { if (s - 1 < 8) YSHIFT(yk0); else if (s - 1 < 16) YSHIFT(yk1); else if (s - 1 < 24) YSHIFT(yk2); else YSHIFT(yk3); }
;                     x = x * si;
;                     f32x2 x2; x2.x = x; asm volatile("" : "+v"(x2));
;                     VPKNFMABL(P01, x2, Rka[c][0].xy, P01); VPKNFMABL(P23, x2, Rka[c][0].zw, P23); VPKNFMABL(P45, x2, Rka[c][1].xy, P45); VPKNFMABL(P67, x2, Rka[c][1].zw, P67);
;                 }
	ds_read_b128 v[64:67], v35 offset:8432
	ds_read_b128 v[76:79], v35 offset:34544
	ds_read_b32 v94, v36 offset:3968
	ds_read_b32 v95, v38 offset:3968
	ds_read_b128 v[68:71], v35 offset:17136
	ds_read_b128 v[72:75], v35 offset:25840
	ds_read_b128 v[84:87], v35 offset:43248
	v_pk_mul_f32 v[8:9], v[0:1], v[48:49] op_sel_hi:[1,0]
	v_pk_mul_f32 v[10:11], v[0:1], v[88:89] op_sel_hi:[1,0]
	v_pk_fma_f32 v[8:9], v[2:3], v[48:49], v[8:9] op_sel:[0,1,0] op_sel_hi:[1,1,1]
	v_pk_fma_f32 v[10:11], v[2:3], v[88:89], v[10:11] op_sel:[0,1,0] op_sel_hi:[1,1,1]
	v_pk_fma_f32 v[8:9], v[4:5], v[50:51], v[8:9] op_sel_hi:[1,0,1]
	v_pk_fma_f32 v[10:11], v[4:5], v[90:91], v[10:11] op_sel_hi:[1,0,1]
	v_pk_fma_f32 v[8:9], v[6:7], v[50:51], v[8:9] op_sel:[0,1,0] op_sel_hi:[1,1,1]
	v_pk_fma_f32 v[10:11], v[6:7], v[90:91], v[10:11] op_sel:[0,1,0] op_sel_hi:[1,1,1]
	v_readlane_b32 s10, v34, 30
	v_pk_mul_f32 v[16:17], v[92:93], v[60:61] op_sel_hi:[1,0]
	v_pk_mul_f32 v[18:19], v[92:93], v[60:61] op_sel:[0,1] op_sel_hi:[1,1]
	v_add_f32_dpp v8, v9, v8 quad_perm:[1,0,3,2] row_mask:0xf bank_mask:0xf bound_ctrl:1
	v_add_f32_dpp v10, v11, v10 quad_perm:[1,0,3,2] row_mask:0xf bank_mask:0xf bound_ctrl:1
	v_pk_mul_f32 v[20:21], v[92:93], v[62:63] op_sel_hi:[1,0]
	v_pk_mul_f32 v[22:23], v[92:93], v[62:63] op_sel:[0,1] op_sel_hi:[1,1]
	v_add_f32_dpp v8, v8, v8 quad_perm:[2,3,0,1] row_mask:0xf bank_mask:0xf bound_ctrl:1
	v_add_f32_dpp v10, v10, v10 quad_perm:[2,3,0,1] row_mask:0xf bank_mask:0xf bound_ctrl:1
	v_pk_fma_f32 v[0:1], v[0:1], v[52:53], v[16:17] op_sel_hi:[1,0,1]
	v_pk_fma_f32 v[2:3], v[2:3], v[52:53], v[18:19] op_sel:[0,1,0] op_sel_hi:[1,1,1]
	v_add_f32_dpp v8, v8, v8 row_ror:4 row_mask:0xf bank_mask:0xf bound_ctrl:1
	v_add_f32_dpp v10, v10, v10 row_ror:4 row_mask:0xf bank_mask:0xf bound_ctrl:1
	v_pk_fma_f32 v[4:5], v[4:5], v[54:55], v[20:21] op_sel_hi:[1,0,1]
	v_add_f32_dpp v8, v8, v8 row_ror:8 row_mask:0xf bank_mask:0xf bound_ctrl:1
	v_mul_f32_e32 v8, s10, v8
	v_add_f32_dpp v103, v10, v10 row_ror:8 row_mask:0xf bank_mask:0x2 bound_ctrl:1
	v_pk_fma_f32 v[6:7], v[6:7], v[54:55], v[22:23] op_sel:[0,1,0] op_sel_hi:[1,1,1]
	v_mov_b32_dpp v9, v8 quad_perm:[1,0,3,2] row_mask:0xf bank_mask:0xf
	v_pk_fma_f32 v[0:1], v[8:9], v[56:57], v[0:1] op_sel_hi:[1,0,1] neg_lo:[1,0,0] neg_hi:[1,0,0]
	v_pk_fma_f32 v[2:3], v[8:9], v[56:57], v[2:3] op_sel:[0,1,0] op_sel_hi:[1,1,1] neg_lo:[1,0,0] neg_hi:[1,0,0]
	v_pk_fma_f32 v[4:5], v[8:9], v[58:59], v[4:5] op_sel_hi:[1,0,1] neg_lo:[1,0,0] neg_hi:[1,0,0]
	v_pk_fma_f32 v[6:7], v[8:9], v[58:59], v[6:7] op_sel:[0,1,0] op_sel_hi:[1,1,1] neg_lo:[1,0,0] neg_hi:[1,0,0]
	s_waitcnt lgkmcnt(0)
	v_pk_mul_f32 v[8:9], v[0:1], v[64:65] op_sel_hi:[1,0]
	v_pk_mul_f32 v[10:11], v[0:1], v[80:81] op_sel_hi:[1,0]
	v_pk_fma_f32 v[8:9], v[2:3], v[64:65], v[8:9] op_sel:[0,1,0] op_sel_hi:[1,1,1]
	v_pk_fma_f32 v[10:11], v[2:3], v[80:81], v[10:11] op_sel:[0,1,0] op_sel_hi:[1,1,1]
	v_pk_fma_f32 v[8:9], v[4:5], v[66:67], v[8:9] op_sel_hi:[1,0,1]
	v_pk_fma_f32 v[10:11], v[4:5], v[82:83], v[10:11] op_sel_hi:[1,0,1]
	v_pk_fma_f32 v[8:9], v[6:7], v[66:67], v[8:9] op_sel:[0,1,0] op_sel_hi:[1,1,1]
	v_pk_fma_f32 v[10:11], v[6:7], v[82:83], v[10:11] op_sel:[0,1,0] op_sel_hi:[1,1,1]
	v_readlane_b32 s10, v34, 31
	v_pk_mul_f32 v[16:17], v[94:95], v[76:77] op_sel_hi:[1,0]
	v_pk_mul_f32 v[18:19], v[94:95], v[76:77] op_sel:[0,1] op_sel_hi:[1,1]
	v_add_f32_dpp v8, v9, v8 quad_perm:[1,0,3,2] row_mask:0xf bank_mask:0xf bound_ctrl:1
	v_add_f32_dpp v10, v11, v10 quad_perm:[1,0,3,2] row_mask:0xf bank_mask:0xf bound_ctrl:1
	v_pk_mul_f32 v[20:21], v[94:95], v[78:79] op_sel_hi:[1,0]
	v_pk_mul_f32 v[22:23], v[94:95], v[78:79] op_sel:[0,1] op_sel_hi:[1,1]
	v_add_f32_dpp v8, v8, v8 quad_perm:[2,3,0,1] row_mask:0xf bank_mask:0xf bound_ctrl:1
	v_add_f32_dpp v10, v10, v10 quad_perm:[2,3,0,1] row_mask:0xf bank_mask:0xf bound_ctrl:1
	v_pk_fma_f32 v[0:1], v[0:1], v[68:69], v[16:17] op_sel_hi:[1,0,1]
	v_pk_fma_f32 v[2:3], v[2:3], v[68:69], v[18:19] op_sel:[0,1,0] op_sel_hi:[1,1,1]
	v_add_f32_dpp v8, v8, v8 row_ror:4 row_mask:0xf bank_mask:0xf bound_ctrl:1
	v_add_f32_dpp v10, v10, v10 row_ror:4 row_mask:0xf bank_mask:0xf bound_ctrl:1
	v_pk_fma_f32 v[4:5], v[4:5], v[70:71], v[20:21] op_sel_hi:[1,0,1]
	v_add_f32_dpp v8, v8, v8 row_ror:8 row_mask:0xf bank_mask:0xf bound_ctrl:1
	v_mul_f32_e32 v8, s10, v8
	v_add_f32_dpp v103, v10, v10 row_ror:8 row_mask:0xf bank_mask:0x4 bound_ctrl:1
	v_pk_fma_f32 v[6:7], v[6:7], v[70:71], v[22:23] op_sel:[0,1,0] op_sel_hi:[1,1,1]
	v_mov_b32_dpp v9, v8 quad_perm:[1,0,3,2] row_mask:0xf bank_mask:0xf
	v_pk_fma_f32 v[0:1], v[8:9], v[72:73], v[0:1] op_sel_hi:[1,0,1] neg_lo:[1,0,0] neg_hi:[1,0,0]
	v_pk_fma_f32 v[2:3], v[8:9], v[72:73], v[2:3] op_sel:[0,1,0] op_sel_hi:[1,1,1] neg_lo:[1,0,0] neg_hi:[1,0,0]
	v_pk_fma_f32 v[4:5], v[8:9], v[74:75], v[4:5] op_sel_hi:[1,0,1] neg_lo:[1,0,0] neg_hi:[1,0,0]
	v_pk_fma_f32 v[6:7], v[8:9], v[74:75], v[6:7] op_sel:[0,1,0] op_sel_hi:[1,1,1] neg_lo:[1,0,0] neg_hi:[1,0,0]
	v_pk_mul_f32 v[10:11], v[0:1], v[84:85] op_sel_hi:[1,0]
	v_pk_fma_f32 v[10:11], v[2:3], v[84:85], v[10:11] op_sel:[0,1,0] op_sel_hi:[1,1,1]
	v_pk_fma_f32 v[10:11], v[4:5], v[86:87], v[10:11] op_sel_hi:[1,0,1]
	v_pk_fma_f32 v[10:11], v[6:7], v[86:87], v[10:11] op_sel:[0,1,0] op_sel_hi:[1,1,1]
	s_nop 1
	v_add_f32_dpp v10, v11, v10 quad_perm:[1,0,3,2] row_mask:0xf bank_mask:0xf bound_ctrl:1
	s_nop 1
	v_add_f32_dpp v10, v10, v10 quad_perm:[2,3,0,1] row_mask:0xf bank_mask:0xf bound_ctrl:1
	s_nop 1
	v_add_f32_dpp v10, v10, v10 row_ror:4 row_mask:0xf bank_mask:0xf bound_ctrl:1
	s_nop 1
	v_add_f32_dpp v103, v10, v10 row_ror:8 row_mask:0xf bank_mask:0x8 bound_ctrl:1
	ds_write_b32 v37, v96 offset:0
	ds_write_b32 v37, v97 offset:512
	ds_write_b32 v37, v98 offset:1024
	ds_write_b32 v37, v99 offset:1536
	ds_write_b32 v37, v100 offset:2048
	ds_write_b32 v37, v101 offset:2560
	ds_write_b32 v37, v102 offset:3072
	ds_write_b32 v37, v103 offset:3584
